# all 9 GEMM k-loops: both halves' LDS fragment reads issued up front into two register sets, counted lgkmcnt per MFMA
# speedup vs baseline: 1.0229x; 1.0149x over previous
.LBB0_231:
	v_lshl_add_u64 v[100:101], v[80:81], 0, s[24:25]
	s_add_i32 s47, s48, 0x8000
	s_and_b32 s27, s48, 0x8000
	s_mov_b64 s[48:49], 0x2200080
	v_lshl_add_u64 v[102:103], v[82:83], 0, s[24:25]
	v_lshl_add_u64 v[104:105], v[100:101], 0, s[48:49]
	s_mov_b64 s[48:49], 0x700080
	v_lshl_add_u64 v[106:107], v[102:103], 0, s[48:49]
	s_mov_b64 s[48:49], 0x2211080
	v_lshl_add_u64 v[108:109], v[100:101], 0, s[48:49]
	s_mov_b64 s[48:49], 0x711080
	s_and_b32 s50, s47, 0x8000
	v_lshl_add_u64 v[110:111], v[102:103], 0, s[48:49]
	s_mov_b64 s[48:49], 0x2222080
	v_lshl_add_u64 v[112:113], v[100:101], 0, s[48:49]
	s_add_i32 s48, s27, 0
	s_add_i32 s27, s50, 0
	v_add_u32_e32 v116, s27, v84
	v_add_u32_e32 v117, 0x4000, v116
	v_readfirstlane_b32 s49, v116
	v_add_u32_e32 v118, 0x1000, v116
	v_readfirstlane_b32 s50, v117
	s_mov_b32 m0, s49
	s_waitcnt vmcnt(0) lgkmcnt(0)
	s_barrier
	v_add_u32_e32 v119, 0x5000, v116
	v_readfirstlane_b32 s51, v118
	global_load_lds_dwordx4 v[104:105], off
	s_mov_b32 m0, s50
	v_add_u32_e32 v120, 0x2000, v116
	v_readfirstlane_b32 s52, v119
	global_load_lds_dwordx4 v[106:107], off
	s_mov_b32 m0, s51
	v_add_u32_e32 v121, 0x6000, v116
	v_readfirstlane_b32 s53, v120
	global_load_lds_dwordx4 v[108:109], off
	s_mov_b32 m0, s52
	v_add_u32_e32 v122, 0x3000, v116
	v_readfirstlane_b32 s54, v121
	global_load_lds_dwordx4 v[110:111], off
	s_mov_b32 m0, s53
	v_lshl_add_u64 v[114:115], v[102:103], 0, s[12:13]
	v_add_u32_e32 v116, 0x7000, v116
	v_readfirstlane_b32 s55, v122
	global_load_lds_dwordx4 v[112:113], off
	s_mov_b32 m0, s54
	v_lshl_add_u64 v[100:101], v[100:101], 0, s[14:15]
	v_readfirstlane_b32 s56, v116
	global_load_lds_dwordx4 v[114:115], off
	s_mov_b32 m0, s55
	v_lshl_add_u64 v[102:103], v[102:103], 0, s[16:17]
	global_load_lds_dwordx4 v[100:101], off
	s_mov_b32 m0, s56
	v_add_u32_e32 v64, s48, v86
	global_load_lds_dwordx4 v[102:103], off
	v_add_u32_e32 v145, v64, v87
	v_add3_u32 v208, s48, v87, v88
	v_add_u32_e32 v209, v64, v89
	v_add3_u32 v210, s48, v88, v89
	ds_read_b128 v[104:107], v208
	ds_read_b128 v[100:103], v145 offset:16384
	ds_read_b128 v[108:111], v145 offset:18432
	ds_read_b128 v[164:167], v208 offset:2048
	ds_read_b128 v[112:115], v145 offset:20480
	ds_read_b128 v[116:119], v145 offset:22528
	ds_read_b128 v[120:123], v145 offset:24576
	ds_read_b128 v[124:127], v145 offset:26624
	ds_read_b128 v[128:131], v145 offset:28672
	ds_read_b128 v[132:135], v145 offset:30720
	ds_read_b128 v[200:203], v210
	ds_read_b128 v[168:171], v209 offset:16384
	ds_read_b128 v[172:175], v209 offset:18432
	ds_read_b128 v[204:207], v210 offset:2048
	ds_read_b128 v[176:179], v209 offset:20480
	ds_read_b128 v[180:183], v209 offset:22528
	ds_read_b128 v[184:187], v209 offset:24576
	ds_read_b128 v[188:191], v209 offset:26624
	ds_read_b128 v[192:195], v209 offset:28672
	ds_read_b128 v[196:199], v209 offset:30720
	s_add_u32 s24, s24, 0x80
	s_addc_u32 s25, s25, 0
	s_cmpk_eq_i32 s24, 0x780
	s_mov_b32 s48, s47
	s_waitcnt lgkmcnt(15)
	v_mfma_f32_16x16x32_bf16 v[60:63], v[100:103], v[104:107], v[60:63]
	v_mfma_f32_16x16x32_bf16 v[56:59], v[108:111], v[104:107], v[56:59]
	v_mfma_f32_16x16x32_bf16 v[24:27], v[100:103], v[164:167], v[24:27]
	v_mfma_f32_16x16x32_bf16 v[20:23], v[108:111], v[164:167], v[20:23]
	v_mfma_f32_16x16x32_bf16 v[52:55], v[112:115], v[104:107], v[52:55]
	v_mfma_f32_16x16x32_bf16 v[16:19], v[112:115], v[164:167], v[16:19]
	s_waitcnt lgkmcnt(14)
	v_mfma_f32_16x16x32_bf16 v[48:51], v[116:119], v[104:107], v[48:51]
	v_mfma_f32_16x16x32_bf16 v[12:15], v[116:119], v[164:167], v[12:15]
	s_waitcnt lgkmcnt(13)
	v_mfma_f32_16x16x32_bf16 v[44:47], v[120:123], v[104:107], v[44:47]
	v_mfma_f32_16x16x32_bf16 v[8:11], v[120:123], v[164:167], v[8:11]
	s_waitcnt lgkmcnt(12)
	v_mfma_f32_16x16x32_bf16 v[40:43], v[124:127], v[104:107], v[40:43]
	v_mfma_f32_16x16x32_bf16 v[4:7], v[124:127], v[164:167], v[4:7]
	s_waitcnt lgkmcnt(11)
	v_mfma_f32_16x16x32_bf16 v[36:39], v[128:131], v[104:107], v[36:39]
	v_mfma_f32_16x16x32_bf16 v[0:3], v[128:131], v[164:167], v[0:3]
	s_waitcnt lgkmcnt(10)
	v_mfma_f32_16x16x32_bf16 v[32:35], v[132:135], v[104:107], v[32:35]
	v_mfma_f32_16x16x32_bf16 v[28:31], v[132:135], v[164:167], v[28:31]
	s_waitcnt lgkmcnt(8)
	v_mfma_f32_16x16x32_bf16 v[60:63], v[168:171], v[200:203], v[60:63]
	s_waitcnt lgkmcnt(7)
	v_mfma_f32_16x16x32_bf16 v[56:59], v[172:175], v[200:203], v[56:59]
	s_waitcnt lgkmcnt(6)
	v_mfma_f32_16x16x32_bf16 v[24:27], v[168:171], v[204:207], v[24:27]
	v_mfma_f32_16x16x32_bf16 v[20:23], v[172:175], v[204:207], v[20:23]
	s_waitcnt lgkmcnt(5)
	v_mfma_f32_16x16x32_bf16 v[52:55], v[176:179], v[200:203], v[52:55]
	v_mfma_f32_16x16x32_bf16 v[16:19], v[176:179], v[204:207], v[16:19]
	s_waitcnt lgkmcnt(4)
	v_mfma_f32_16x16x32_bf16 v[48:51], v[180:183], v[200:203], v[48:51]
	v_mfma_f32_16x16x32_bf16 v[12:15], v[180:183], v[204:207], v[12:15]
	s_waitcnt lgkmcnt(3)
	v_mfma_f32_16x16x32_bf16 v[44:47], v[184:187], v[200:203], v[44:47]
	v_mfma_f32_16x16x32_bf16 v[8:11], v[184:187], v[204:207], v[8:11]
	s_waitcnt lgkmcnt(2)
	v_mfma_f32_16x16x32_bf16 v[40:43], v[188:191], v[200:203], v[40:43]
	v_mfma_f32_16x16x32_bf16 v[4:7], v[188:191], v[204:207], v[4:7]
	s_waitcnt lgkmcnt(1)
	v_mfma_f32_16x16x32_bf16 v[36:39], v[192:195], v[200:203], v[36:39]
	v_mfma_f32_16x16x32_bf16 v[0:3], v[192:195], v[204:207], v[0:3]
	s_waitcnt lgkmcnt(0)
	v_mfma_f32_16x16x32_bf16 v[32:35], v[196:199], v[200:203], v[32:35]
	v_mfma_f32_16x16x32_bf16 v[28:31], v[196:199], v[204:207], v[28:31]
	s_cbranch_scc0 .LBB0_231
	v_add_u32_e32 v64, s27, v86
	v_add_u32_e32 v136, v64, v87
	v_add3_u32 v108, s27, v87, v88
	s_waitcnt vmcnt(0)
	s_barrier
	ds_read_b128 v[80:83], v136 offset:16384
	ds_read_b128 v[100:103], v136 offset:18432
	ds_read_b128 v[104:107], v108
	ds_read_b128 v[108:111], v108 offset:2048
	ds_read_b128 v[112:115], v136 offset:20480
	ds_read_b128 v[116:119], v136 offset:22528
	ds_read_b128 v[128:131], v136 offset:28672
	s_waitcnt lgkmcnt(2)
	v_mfma_f32_16x16x32_bf16 v[120:123], v[112:115], v[104:107], v[52:55]
	s_nop 2
	ds_read_b128 v[52:55], v136 offset:24576
	ds_read_b128 v[124:127], v136 offset:26624
	s_cmp_gt_i32 s26, 11
	s_waitcnt lgkmcnt(0)
	v_mfma_f32_16x16x32_bf16 v[132:135], v[124:127], v[104:107], v[40:43]
	s_nop 2
	ds_read_b128 v[40:43], v136 offset:30720
	s_cselect_b64 s[24:25], -1, 0
	s_cmp_lt_i32 s26, 12
	v_mfma_f32_16x16x32_bf16 v[60:63], v[80:83], v[104:107], v[60:63]
	s_cselect_b64 s[48:49], -1, 0
	v_mfma_f32_16x16x32_bf16 v[56:59], v[100:103], v[104:107], v[56:59]
	v_mfma_f32_16x16x32_bf16 v[48:51], v[116:119], v[104:107], v[48:51]
	v_mfma_f32_16x16x32_bf16 v[44:47], v[52:55], v[104:107], v[44:47]
	v_mfma_f32_16x16x32_bf16 v[136:139], v[128:131], v[104:107], v[36:39]
	s_waitcnt lgkmcnt(0)
	v_mfma_f32_16x16x32_bf16 v[32:35], v[40:43], v[104:107], v[32:35]
	v_mfma_f32_16x16x32_bf16 v[104:107], v[52:55], v[108:111], v[8:11]
	s_nop 2
	v_add_u32_e32 v8, v64, v89
	v_mfma_f32_16x16x32_bf16 v[24:27], v[80:83], v[108:111], v[24:27]
	v_add3_u32 v9, s27, v89, v88
	v_lshl_or_b32 v64, s26, 7, v90
	s_sub_i32 s26, s26, 18
	v_mfma_f32_16x16x32_bf16 v[80:83], v[112:115], v[108:111], v[16:19]
	s_cmp_lt_u32 s26, 8
	s_cselect_b64 s[26:27], -1, 0
	s_or_b64 s[48:49], s[48:49], s[26:27]
	v_mfma_f32_16x16x32_bf16 v[112:115], v[124:127], v[108:111], v[4:7]
	s_mov_b64 s[26:27], -1
	s_andn2_b64 vcc, exec, s[48:49]
	s_nop 0
	ds_read_b128 v[4:7], v8 offset:16384
	v_mfma_f32_16x16x32_bf16 v[20:23], v[100:103], v[108:111], v[20:23]
	v_mfma_f32_16x16x32_bf16 v[100:103], v[116:119], v[108:111], v[12:15]
	v_mfma_f32_16x16x32_bf16 v[116:119], v[128:131], v[108:111], v[0:3]
	ds_read_b128 v[124:127], v8 offset:18432
	s_nop 1
	ds_read_b128 v[0:3], v9
	ds_read_b128 v[128:131], v9 offset:2048
	ds_read_b128 v[140:143], v8 offset:22528
	ds_read_b128 v[146:149], v8 offset:28672
	s_waitcnt lgkmcnt(3)
	v_mfma_f32_16x16x32_bf16 v[52:55], v[4:7], v[0:3], v[60:63]
	s_nop 2
	ds_read_b128 v[60:63], v8 offset:20480
	v_mfma_f32_16x16x32_bf16 v[108:111], v[40:43], v[108:111], v[28:31]
	s_waitcnt lgkmcnt(0)
	v_mfma_f32_16x16x32_bf16 v[36:39], v[60:63], v[0:3], v[120:123]
	s_nop 2
	ds_read_b128 v[120:123], v8 offset:24576
	v_mfma_f32_16x16x32_bf16 v[40:43], v[140:143], v[0:3], v[48:51]
	s_nop 2
	ds_read_b128 v[48:51], v8 offset:26624
	s_waitcnt lgkmcnt(0)
	v_mfma_f32_16x16x32_bf16 v[16:19], v[48:51], v[0:3], v[132:135]
	s_nop 2
	ds_read_b128 v[132:135], v8 offset:30720
	v_mfma_f32_16x16x32_bf16 v[56:59], v[124:127], v[0:3], v[56:59]
	v_mfma_f32_16x16x32_bf16 v[12:15], v[120:123], v[0:3], v[44:47]
	v_mfma_f32_16x16x32_bf16 v[8:11], v[146:149], v[0:3], v[136:139]
	s_waitcnt lgkmcnt(0)
	v_mfma_f32_16x16x32_bf16 v[0:3], v[132:135], v[0:3], v[32:35]
	v_mfma_f32_16x16x32_bf16 v[28:31], v[4:7], v[128:131], v[24:27]
	v_mfma_f32_16x16x32_bf16 v[20:23], v[124:127], v[128:131], v[20:23]
	v_mfma_f32_16x16x32_bf16 v[4:7], v[60:63], v[128:131], v[80:83]
	v_mfma_f32_16x16x32_bf16 v[24:27], v[140:143], v[128:131], v[100:103]
	s_nop 1
	v_lshl_add_u32 v80, s46, 7, v85
	v_mfma_f32_16x16x32_bf16 v[32:35], v[120:123], v[128:131], v[104:107]
	v_mfma_f32_16x16x32_bf16 v[44:47], v[48:51], v[128:131], v[112:115]
	v_mfma_f32_16x16x32_bf16 v[48:51], v[146:149], v[128:131], v[116:119]
	v_mfma_f32_16x16x32_bf16 v[60:63], v[132:135], v[128:131], v[108:111]
	s_cbranch_vccz .LBB0_240
	s_and_b32 s47, 0xffff, s45
	s_cmp_gt_u32 s47, 17
	s_cbranch_scc0 .LBB0_237
	s_cmp_eq_u32 s47, 26
	s_cselect_b64 s[26:27], -1, 0
	s_and_b64 s[48:49], s[10:11], s[26:27]
	s_and_saveexec_b64 s[26:27], s[48:49]
	s_cbranch_execz .LBB0_236
	global_load_dwordx4 v[100:103], v[72:73], off
	v_mad_i64_i32 v[82:83], s[48:49], v80, s28, v[70:71]
	v_or_b32_e32 v81, 16, v80
	s_waitcnt vmcnt(0)
	v_pk_add_f32 v[102:103], v[54:55], v[102:103]
	v_pk_add_f32 v[100:101], v[52:53], v[100:101]
	global_store_dwordx4 v[82:83], v[100:103], off
	global_load_dwordx4 v[100:103], v[72:73], off offset:16
	v_mad_i64_i32 v[82:83], s[48:49], v80, s28, v[74:75]
	s_waitcnt vmcnt(0)
	v_pk_add_f32 v[102:103], v[58:59], v[102:103]
	v_pk_add_f32 v[100:101], v[56:57], v[100:101]
	global_store_dwordx4 v[82:83], v[100:103], off
	global_load_dwordx4 v[100:103], v[72:73], off
	v_mad_i64_i32 v[82:83], s[48:49], v81, s28, v[70:71]
	s_waitcnt vmcnt(0)
	v_pk_add_f32 v[102:103], v[30:31], v[102:103]
	v_pk_add_f32 v[100:101], v[28:29], v[100:101]
	global_store_dwordx4 v[82:83], v[100:103], off
	global_load_dwordx4 v[100:103], v[72:73], off offset:16
	v_mad_i64_i32 v[82:83], s[48:49], v81, s28, v[74:75]
	s_waitcnt vmcnt(0)
	v_pk_add_f32 v[102:103], v[22:23], v[102:103]
	v_pk_add_f32 v[100:101], v[20:21], v[100:101]
	global_store_dwordx4 v[82:83], v[100:103], off

.LBB0_855:
	s_add_i32 s45, s43, 0x8000
	s_and_b32 s44, s45, 0x8000
	s_add_i32 s44, s44, 0
	v_add_u32_e32 v113, s44, v87
	v_lshl_add_u64 v[76:77], v[72:73], 0, s[34:35]
	v_readfirstlane_b32 s46, v113
	v_add_u32_e32 v114, 0x4000, v113
	v_lshl_add_u64 v[78:79], v[74:75], 0, s[34:35]
	v_lshl_add_u64 v[80:81], v[76:77], 0, s[14:15]
	v_add_u32_e32 v115, 0x1000, v113
	v_readfirstlane_b32 s47, v114
	s_mov_b32 m0, s46
	s_waitcnt vmcnt(0) lgkmcnt(0)
	s_barrier
	v_lshl_add_u64 v[102:103], v[78:79], 0, s[16:17]
	v_add_u32_e32 v116, 0x5000, v113
	v_readfirstlane_b32 s48, v115
	global_load_lds_dwordx4 v[80:81], off
	s_mov_b32 m0, s47
	v_lshl_add_u64 v[104:105], v[76:77], 0, s[18:19]
	v_add_u32_e32 v117, 0x2000, v113
	v_readfirstlane_b32 s49, v116
	global_load_lds_dwordx4 v[102:103], off
	s_mov_b32 m0, s48
	v_lshl_add_u64 v[106:107], v[78:79], 0, s[20:21]
	v_add_u32_e32 v118, 0x6000, v113
	v_readfirstlane_b32 s50, v117
	global_load_lds_dwordx4 v[104:105], off
	s_mov_b32 m0, s49
	v_lshl_add_u64 v[108:109], v[76:77], 0, s[22:23]
	v_add_u32_e32 v119, 0x3000, v113
	v_readfirstlane_b32 s51, v118
	global_load_lds_dwordx4 v[106:107], off
	s_mov_b32 m0, s50
	v_lshl_add_u64 v[110:111], v[78:79], 0, s[24:25]
	v_add_u32_e32 v113, 0x7000, v113
	v_readfirstlane_b32 s52, v119
	global_load_lds_dwordx4 v[108:109], off
	s_mov_b32 m0, s51
	v_lshl_add_u64 v[76:77], v[76:77], 0, s[26:27]
	v_readfirstlane_b32 s53, v113
	global_load_lds_dwordx4 v[110:111], off
	s_mov_b32 m0, s52
	v_lshl_add_u64 v[78:79], v[78:79], 0, s[28:29]
	global_load_lds_dwordx4 v[76:77], off
	s_mov_b32 m0, s53
	s_and_b32 s43, s43, 0x8000
	global_load_lds_dwordx4 v[78:79], off
	s_add_i32 s43, s43, 0
	v_add3_u32 v212, s43, v88, v89
	v_add3_u32 v213, s43, v89, v90
	v_add3_u32 v214, s43, v88, v91
	v_add3_u32 v215, s43, v90, v91
	ds_read_b128 v[106:109], v213
	ds_read_b128 v[76:79], v212 offset:16384
	ds_read_b128 v[102:105], v212 offset:18432
	ds_read_b128 v[110:113], v213 offset:2048
	ds_read_b128 v[114:117], v212 offset:20480
	ds_read_b128 v[118:121], v212 offset:22528
	ds_read_b128 v[122:125], v212 offset:24576
	ds_read_b128 v[126:129], v212 offset:26624
	ds_read_b128 v[130:133], v212 offset:28672
	ds_read_b128 v[134:137], v212 offset:30720
	ds_read_b128 v[180:183], v215
	ds_read_b128 v[172:175], v214 offset:16384
	ds_read_b128 v[176:179], v214 offset:18432
	ds_read_b128 v[184:187], v215 offset:2048
	ds_read_b128 v[188:191], v214 offset:20480
	ds_read_b128 v[192:195], v214 offset:22528
	ds_read_b128 v[196:199], v214 offset:24576
	ds_read_b128 v[200:203], v214 offset:26624
	ds_read_b128 v[204:207], v214 offset:28672
	ds_read_b128 v[208:211], v214 offset:30720
	s_add_u32 s34, s34, 0x80
	s_addc_u32 s35, s35, 0
	s_cmpk_eq_i32 s34, 0x780
	s_mov_b32 s43, s45
	s_waitcnt lgkmcnt(15)
	v_mfma_f32_16x16x32_bf16 v[60:63], v[76:79], v[106:109], v[60:63]
	v_mfma_f32_16x16x32_bf16 v[56:59], v[102:105], v[106:109], v[56:59]
	v_mfma_f32_16x16x32_bf16 v[24:27], v[76:79], v[110:113], v[24:27]
	v_mfma_f32_16x16x32_bf16 v[20:23], v[102:105], v[110:113], v[20:23]
	v_mfma_f32_16x16x32_bf16 v[52:55], v[114:117], v[106:109], v[52:55]
	v_mfma_f32_16x16x32_bf16 v[16:19], v[114:117], v[110:113], v[16:19]
	s_waitcnt lgkmcnt(14)
	v_mfma_f32_16x16x32_bf16 v[48:51], v[118:121], v[106:109], v[48:51]
	v_mfma_f32_16x16x32_bf16 v[12:15], v[118:121], v[110:113], v[12:15]
	s_waitcnt lgkmcnt(13)
	v_mfma_f32_16x16x32_bf16 v[44:47], v[122:125], v[106:109], v[44:47]
	v_mfma_f32_16x16x32_bf16 v[8:11], v[122:125], v[110:113], v[8:11]
	s_waitcnt lgkmcnt(12)
	v_mfma_f32_16x16x32_bf16 v[40:43], v[126:129], v[106:109], v[40:43]
	v_mfma_f32_16x16x32_bf16 v[4:7], v[126:129], v[110:113], v[4:7]
	s_waitcnt lgkmcnt(11)
	v_mfma_f32_16x16x32_bf16 v[32:35], v[130:133], v[106:109], v[32:35]
	v_mfma_f32_16x16x32_bf16 v[0:3], v[130:133], v[110:113], v[0:3]
	s_waitcnt lgkmcnt(10)
	v_mfma_f32_16x16x32_bf16 v[28:31], v[134:137], v[106:109], v[28:31]
	v_mfma_f32_16x16x32_bf16 v[36:39], v[134:137], v[110:113], v[36:39]
	s_waitcnt lgkmcnt(8)
	v_mfma_f32_16x16x32_bf16 v[60:63], v[172:175], v[180:183], v[60:63]
	s_waitcnt lgkmcnt(7)
	v_mfma_f32_16x16x32_bf16 v[56:59], v[176:179], v[180:183], v[56:59]
	s_waitcnt lgkmcnt(6)
	v_mfma_f32_16x16x32_bf16 v[24:27], v[172:175], v[184:187], v[24:27]
	v_mfma_f32_16x16x32_bf16 v[20:23], v[176:179], v[184:187], v[20:23]
	s_waitcnt lgkmcnt(5)
	v_mfma_f32_16x16x32_bf16 v[52:55], v[188:191], v[180:183], v[52:55]
	v_mfma_f32_16x16x32_bf16 v[16:19], v[188:191], v[184:187], v[16:19]
	s_waitcnt lgkmcnt(4)
	v_mfma_f32_16x16x32_bf16 v[48:51], v[192:195], v[180:183], v[48:51]
	v_mfma_f32_16x16x32_bf16 v[12:15], v[192:195], v[184:187], v[12:15]
	s_waitcnt lgkmcnt(3)
	v_mfma_f32_16x16x32_bf16 v[44:47], v[196:199], v[180:183], v[44:47]
	v_mfma_f32_16x16x32_bf16 v[8:11], v[196:199], v[184:187], v[8:11]
	s_waitcnt lgkmcnt(2)
	v_mfma_f32_16x16x32_bf16 v[40:43], v[200:203], v[180:183], v[40:43]
	v_mfma_f32_16x16x32_bf16 v[4:7], v[200:203], v[184:187], v[4:7]
	s_waitcnt lgkmcnt(1)
	v_mfma_f32_16x16x32_bf16 v[32:35], v[204:207], v[180:183], v[32:35]
	v_mfma_f32_16x16x32_bf16 v[0:3], v[204:207], v[184:187], v[0:3]
	s_waitcnt lgkmcnt(0)
	v_mfma_f32_16x16x32_bf16 v[28:31], v[208:211], v[180:183], v[28:31]
	v_mfma_f32_16x16x32_bf16 v[36:39], v[208:211], v[184:187], v[36:39]
	s_cbranch_scc0 .LBB0_855
	v_add_u32_e32 v80, s44, v88
	v_add_u32_e32 v81, v80, v89
	v_add3_u32 v106, s44, v89, v90
	s_waitcnt vmcnt(0)
	s_barrier
	ds_read_b128 v[72:75], v81 offset:16384
	ds_read_b128 v[76:79], v81 offset:18432
	ds_read_b128 v[102:105], v106
	ds_read_b128 v[106:109], v106 offset:2048
	ds_read_b128 v[110:113], v81 offset:20480
	ds_read_b128 v[114:117], v81 offset:22528
	ds_read_b128 v[118:121], v81 offset:24576
	ds_read_b128 v[122:125], v81 offset:26624
	ds_read_b128 v[126:129], v81 offset:28672
	ds_read_b128 v[130:133], v81 offset:30720
	v_add_u32_e32 v80, v80, v91
	s_waitcnt lgkmcnt(7)
	v_mfma_f32_16x16x32_bf16 v[60:63], v[72:75], v[102:105], v[60:63]
	s_lshl_b32 s42, s42, 7
	v_mfma_f32_16x16x32_bf16 v[56:59], v[76:79], v[102:105], v[56:59]
	s_waitcnt lgkmcnt(4)
	v_mfma_f32_16x16x32_bf16 v[48:51], v[114:117], v[102:105], v[48:51]
	s_waitcnt lgkmcnt(3)
	v_mfma_f32_16x16x32_bf16 v[44:47], v[118:121], v[102:105], v[44:47]
	s_waitcnt lgkmcnt(2)
	v_mfma_f32_16x16x32_bf16 v[40:43], v[122:125], v[102:105], v[40:43]
	s_waitcnt lgkmcnt(1)
	v_mfma_f32_16x16x32_bf16 v[32:35], v[126:129], v[102:105], v[32:35]
	s_waitcnt lgkmcnt(0)
	v_mfma_f32_16x16x32_bf16 v[28:31], v[130:133], v[102:105], v[28:31]
	v_mfma_f32_16x16x32_bf16 v[24:27], v[72:75], v[106:109], v[24:27]
	ds_read_b128 v[72:75], v80 offset:16384
	v_mfma_f32_16x16x32_bf16 v[52:55], v[110:113], v[102:105], v[52:55]
	v_mfma_f32_16x16x32_bf16 v[20:23], v[76:79], v[106:109], v[20:23]
	v_mfma_f32_16x16x32_bf16 v[16:19], v[110:113], v[106:109], v[16:19]
	v_mfma_f32_16x16x32_bf16 v[12:15], v[114:117], v[106:109], v[12:15]
	v_mfma_f32_16x16x32_bf16 v[8:11], v[118:121], v[106:109], v[8:11]
	v_mfma_f32_16x16x32_bf16 v[4:7], v[122:125], v[106:109], v[4:7]
	v_mfma_f32_16x16x32_bf16 v[0:3], v[126:129], v[106:109], v[0:3]
	v_mfma_f32_16x16x32_bf16 v[102:105], v[130:133], v[106:109], v[36:39]
	s_nop 2
	v_add3_u32 v36, s44, v91, v90
	ds_read_b128 v[76:79], v80 offset:18432
	ds_read_b128 v[106:109], v36
	ds_read_b128 v[110:113], v36 offset:2048
	ds_read_b128 v[130:133], v80 offset:28672
	ds_read_b128 v[134:137], v80 offset:30720
	ds_read_b128 v[114:117], v80 offset:20480
	ds_read_b128 v[118:121], v80 offset:22528
	ds_read_b128 v[122:125], v80 offset:24576
	ds_read_b128 v[126:129], v80 offset:26624
	s_waitcnt lgkmcnt(7)
	v_mfma_f32_16x16x32_bf16 v[60:63], v[72:75], v[106:109], v[60:63]
	v_readlane_b32 s44, v252, 5
	v_readlane_b32 s48, v252, 9
	v_readlane_b32 s49, v252, 10
	s_waitcnt lgkmcnt(5)
	v_mfma_f32_16x16x32_bf16 v[36:39], v[130:133], v[106:109], v[32:35]
	v_readlane_b32 s45, v252, 6
	v_readlane_b32 s46, v252, 7
	v_readlane_b32 s47, v252, 8
	s_waitcnt lgkmcnt(4)
	v_mfma_f32_16x16x32_bf16 v[32:35], v[134:137], v[106:109], v[28:31]
	v_readlane_b32 s50, v252, 11
	v_readlane_b32 s51, v252, 12
	v_readlane_b32 s52, v252, 13
	v_mfma_f32_16x16x32_bf16 v[28:31], v[72:75], v[110:113], v[24:27]
	v_add_u32_e32 v72, s42, v82
	v_mul_hi_i32 v73, v72, s36
	v_lshrrev_b32_e32 v74, 31, v73
	v_mfma_f32_16x16x32_bf16 v[24:27], v[76:79], v[110:113], v[20:23]
	v_readlane_b32 s53, v252, 14
	v_readlane_b32 s54, v252, 15
	v_readlane_b32 s55, v252, 16
	s_waitcnt lgkmcnt(3)
	v_mfma_f32_16x16x32_bf16 v[20:23], v[114:117], v[110:113], v[16:19]
	v_readlane_b32 s56, v252, 17
	v_readlane_b32 s57, v252, 18
	v_readlane_b32 s58, v252, 19
	s_waitcnt lgkmcnt(2)
	v_mfma_f32_16x16x32_bf16 v[16:19], v[118:121], v[110:113], v[12:15]
	v_readlane_b32 s59, v252, 20
	s_waitcnt lgkmcnt(1)
	v_mfma_f32_16x16x32_bf16 v[12:15], v[122:125], v[110:113], v[8:11]
	s_waitcnt lgkmcnt(0)
	v_mfma_f32_16x16x32_bf16 v[8:11], v[126:129], v[110:113], v[4:7]
	s_nop 2
	v_ashrrev_i32_e32 v4, 11, v73
	v_mfma_f32_16x16x32_bf16 v[56:59], v[76:79], v[106:109], v[56:59]
	v_add_u32_e32 v73, v4, v74
	v_mad_i32_i24 v75, v73, s37, v72
	v_lshlrev_b32_e32 v78, 13, v73
	v_mfma_f32_16x16x32_bf16 v[52:55], v[114:117], v[106:109], v[52:55]
	v_cmp_lt_i32_e32 vcc, s38, v75
	v_mov_b64_e32 v[76:77], s[48:49]
	v_add3_u32 v74, v78, v75, s39
	v_mfma_f32_16x16x32_bf16 v[48:51], v[118:121], v[106:109], v[48:51]
	v_mfma_f32_16x16x32_bf16 v[44:47], v[122:125], v[106:109], v[44:47]
	v_mfma_f32_16x16x32_bf16 v[40:43], v[126:129], v[106:109], v[40:43]
	v_mfma_f32_16x16x32_bf16 v[0:3], v[130:133], v[110:113], v[0:3]
	v_mfma_f32_16x16x32_bf16 v[4:7], v[134:137], v[110:113], v[102:105]
	s_and_saveexec_b64 s[34:35], vcc
	s_xor_b64 s[34:35], exec, s[34:35]
	s_cbranch_execz .LBB0_858
	v_readlane_b32 s44, v252, 5
	v_readlane_b32 s45, v252, 6
	v_add3_u32 v72, v78, v75, s39
	v_readlane_b32 s46, v252, 7
	v_readlane_b32 s47, v252, 8
	v_readlane_b32 s48, v252, 9
	v_readlane_b32 s49, v252, 10
	v_readlane_b32 s50, v252, 11
	v_readlane_b32 s51, v252, 12
	v_readlane_b32 s52, v252, 13
	v_readlane_b32 s53, v252, 14
	v_readlane_b32 s54, v252, 15
	v_readlane_b32 s55, v252, 16
	v_readlane_b32 s56, v252, 17
	v_readlane_b32 s57, v252, 18
	v_readlane_b32 s58, v252, 19
	v_readlane_b32 s59, v252, 20
	v_mov_b64_e32 v[76:77], s[44:45]
	s_or_saveexec_b64 s[34:35], s[34:35]
	v_lshl_add_u32 v102, v73, 8, v75
	s_xor_b64 exec, exec, s[34:35]
	s_branch .LBB0_859

.LBB0_1071:
	s_add_i32 s45, s43, 0x8000
	s_and_b32 s44, s45, 0x8000
	s_add_i32 s44, s44, 0
	v_add_u32_e32 v113, s44, v88
	v_lshl_add_u64 v[76:77], v[72:73], 0, s[34:35]
	v_readfirstlane_b32 s46, v113
	v_add_u32_e32 v114, 0x4000, v113
	v_lshl_add_u64 v[78:79], v[74:75], 0, s[34:35]
	v_lshl_add_u64 v[80:81], v[76:77], 0, s[14:15]
	v_add_u32_e32 v115, 0x1000, v113
	v_readfirstlane_b32 s47, v114
	s_mov_b32 m0, s46
	s_waitcnt vmcnt(0) lgkmcnt(0)
	s_barrier
	v_lshl_add_u64 v[102:103], v[78:79], 0, s[16:17]
	v_add_u32_e32 v116, 0x5000, v113
	v_readfirstlane_b32 s48, v115
	global_load_lds_dwordx4 v[80:81], off
	s_mov_b32 m0, s47
	v_lshl_add_u64 v[104:105], v[76:77], 0, s[18:19]
	v_add_u32_e32 v117, 0x2000, v113
	v_readfirstlane_b32 s49, v116
	global_load_lds_dwordx4 v[102:103], off
	s_mov_b32 m0, s48
	v_lshl_add_u64 v[106:107], v[78:79], 0, s[20:21]
	v_add_u32_e32 v118, 0x6000, v113
	v_readfirstlane_b32 s50, v117
	global_load_lds_dwordx4 v[104:105], off
	s_mov_b32 m0, s49
	v_lshl_add_u64 v[108:109], v[76:77], 0, s[22:23]
	v_add_u32_e32 v119, 0x3000, v113
	v_readfirstlane_b32 s51, v118
	global_load_lds_dwordx4 v[106:107], off
	s_mov_b32 m0, s50
	v_lshl_add_u64 v[110:111], v[78:79], 0, s[24:25]
	v_add_u32_e32 v113, 0x7000, v113
	v_readfirstlane_b32 s52, v119
	global_load_lds_dwordx4 v[108:109], off
	s_mov_b32 m0, s51
	v_lshl_add_u64 v[76:77], v[76:77], 0, s[26:27]
	v_readfirstlane_b32 s53, v113
	global_load_lds_dwordx4 v[110:111], off
	s_mov_b32 m0, s52
	v_lshl_add_u64 v[78:79], v[78:79], 0, s[28:29]
	global_load_lds_dwordx4 v[76:77], off
	s_mov_b32 m0, s53
	s_and_b32 s43, s43, 0x8000
	global_load_lds_dwordx4 v[78:79], off
	s_add_i32 s43, s43, 0
	v_add3_u32 v169, s43, v84, v89
	v_add3_u32 v210, s43, v89, v90
	v_add3_u32 v211, s43, v84, v91
	v_add3_u32 v212, s43, v90, v91
	ds_read_b128 v[106:109], v210
	ds_read_b128 v[76:79], v169 offset:16384
	ds_read_b128 v[102:105], v169 offset:18432
	ds_read_b128 v[110:113], v210 offset:2048
	ds_read_b128 v[114:117], v169 offset:20480
	ds_read_b128 v[118:121], v169 offset:22528
	ds_read_b128 v[122:125], v169 offset:24576
	ds_read_b128 v[126:129], v169 offset:26624
	ds_read_b128 v[130:133], v169 offset:28672
	ds_read_b128 v[134:137], v169 offset:30720
	ds_read_b128 v[178:181], v212
	ds_read_b128 v[170:173], v211 offset:16384
	ds_read_b128 v[174:177], v211 offset:18432
	ds_read_b128 v[182:185], v212 offset:2048
	ds_read_b128 v[186:189], v211 offset:20480
	ds_read_b128 v[190:193], v211 offset:22528
	ds_read_b128 v[194:197], v211 offset:24576
	ds_read_b128 v[198:201], v211 offset:26624
	ds_read_b128 v[202:205], v211 offset:28672
	ds_read_b128 v[206:209], v211 offset:30720
	s_add_u32 s34, s34, 0x80
	s_addc_u32 s35, s35, 0
	s_cmpk_eq_i32 s34, 0x1f80
	s_mov_b32 s43, s45
	s_waitcnt lgkmcnt(15)
	v_mfma_f32_16x16x32_bf16 v[60:63], v[76:79], v[106:109], v[60:63]
	v_mfma_f32_16x16x32_bf16 v[56:59], v[102:105], v[106:109], v[56:59]
	v_mfma_f32_16x16x32_bf16 v[24:27], v[76:79], v[110:113], v[24:27]
	v_mfma_f32_16x16x32_bf16 v[20:23], v[102:105], v[110:113], v[20:23]
	v_mfma_f32_16x16x32_bf16 v[52:55], v[114:117], v[106:109], v[52:55]
	v_mfma_f32_16x16x32_bf16 v[16:19], v[114:117], v[110:113], v[16:19]
	s_waitcnt lgkmcnt(14)
	v_mfma_f32_16x16x32_bf16 v[48:51], v[118:121], v[106:109], v[48:51]
	v_mfma_f32_16x16x32_bf16 v[12:15], v[118:121], v[110:113], v[12:15]
	s_waitcnt lgkmcnt(13)
	v_mfma_f32_16x16x32_bf16 v[44:47], v[122:125], v[106:109], v[44:47]
	v_mfma_f32_16x16x32_bf16 v[8:11], v[122:125], v[110:113], v[8:11]
	s_waitcnt lgkmcnt(12)
	v_mfma_f32_16x16x32_bf16 v[40:43], v[126:129], v[106:109], v[40:43]
	v_mfma_f32_16x16x32_bf16 v[4:7], v[126:129], v[110:113], v[4:7]
	s_waitcnt lgkmcnt(11)
	v_mfma_f32_16x16x32_bf16 v[32:35], v[130:133], v[106:109], v[32:35]
	v_mfma_f32_16x16x32_bf16 v[0:3], v[130:133], v[110:113], v[0:3]
	s_waitcnt lgkmcnt(10)
	v_mfma_f32_16x16x32_bf16 v[28:31], v[134:137], v[106:109], v[28:31]
	v_mfma_f32_16x16x32_bf16 v[36:39], v[134:137], v[110:113], v[36:39]
	s_waitcnt lgkmcnt(8)
	v_mfma_f32_16x16x32_bf16 v[60:63], v[170:173], v[178:181], v[60:63]
	s_waitcnt lgkmcnt(7)
	v_mfma_f32_16x16x32_bf16 v[56:59], v[174:177], v[178:181], v[56:59]
	s_waitcnt lgkmcnt(6)
	v_mfma_f32_16x16x32_bf16 v[24:27], v[170:173], v[182:185], v[24:27]
	v_mfma_f32_16x16x32_bf16 v[20:23], v[174:177], v[182:185], v[20:23]
	s_waitcnt lgkmcnt(5)
	v_mfma_f32_16x16x32_bf16 v[52:55], v[186:189], v[178:181], v[52:55]
	v_mfma_f32_16x16x32_bf16 v[16:19], v[186:189], v[182:185], v[16:19]
	s_waitcnt lgkmcnt(4)
	v_mfma_f32_16x16x32_bf16 v[48:51], v[190:193], v[178:181], v[48:51]
	v_mfma_f32_16x16x32_bf16 v[12:15], v[190:193], v[182:185], v[12:15]
	s_waitcnt lgkmcnt(3)
	v_mfma_f32_16x16x32_bf16 v[44:47], v[194:197], v[178:181], v[44:47]
	v_mfma_f32_16x16x32_bf16 v[8:11], v[194:197], v[182:185], v[8:11]
	s_waitcnt lgkmcnt(2)
	v_mfma_f32_16x16x32_bf16 v[40:43], v[198:201], v[178:181], v[40:43]
	v_mfma_f32_16x16x32_bf16 v[4:7], v[198:201], v[182:185], v[4:7]
	s_waitcnt lgkmcnt(1)
	v_mfma_f32_16x16x32_bf16 v[32:35], v[202:205], v[178:181], v[32:35]
	v_mfma_f32_16x16x32_bf16 v[0:3], v[202:205], v[182:185], v[0:3]
	s_waitcnt lgkmcnt(0)
	v_mfma_f32_16x16x32_bf16 v[28:31], v[206:209], v[178:181], v[28:31]
	v_mfma_f32_16x16x32_bf16 v[36:39], v[206:209], v[182:185], v[36:39]
	s_cbranch_scc0 .LBB0_1071
	v_add_u32_e32 v80, s44, v84
	v_add_u32_e32 v81, v80, v89
	v_add3_u32 v106, s44, v89, v90
	s_waitcnt vmcnt(0)
	s_barrier
	ds_read_b128 v[72:75], v81 offset:16384
	ds_read_b128 v[76:79], v81 offset:18432
	ds_read_b128 v[102:105], v106
	ds_read_b128 v[106:109], v106 offset:2048
	ds_read_b128 v[110:113], v81 offset:20480
	ds_read_b128 v[114:117], v81 offset:22528
	ds_read_b128 v[118:121], v81 offset:24576
	ds_read_b128 v[122:125], v81 offset:26624
	ds_read_b128 v[126:129], v81 offset:28672
	ds_read_b128 v[130:133], v81 offset:30720
	v_add_u32_e32 v80, v80, v91
	s_waitcnt lgkmcnt(7)
	v_mfma_f32_16x16x32_bf16 v[60:63], v[72:75], v[102:105], v[60:63]
	s_lshl_b32 s42, s42, 7
	v_mfma_f32_16x16x32_bf16 v[56:59], v[76:79], v[102:105], v[56:59]
	s_waitcnt lgkmcnt(4)
	v_mfma_f32_16x16x32_bf16 v[48:51], v[114:117], v[102:105], v[48:51]
	s_waitcnt lgkmcnt(3)
	v_mfma_f32_16x16x32_bf16 v[44:47], v[118:121], v[102:105], v[44:47]
	s_waitcnt lgkmcnt(2)
	v_mfma_f32_16x16x32_bf16 v[40:43], v[122:125], v[102:105], v[40:43]
	s_waitcnt lgkmcnt(1)
	v_mfma_f32_16x16x32_bf16 v[32:35], v[126:129], v[102:105], v[32:35]
	s_waitcnt lgkmcnt(0)
	v_mfma_f32_16x16x32_bf16 v[28:31], v[130:133], v[102:105], v[28:31]
	v_mfma_f32_16x16x32_bf16 v[24:27], v[72:75], v[106:109], v[24:27]
	ds_read_b128 v[72:75], v80 offset:16384
	v_mfma_f32_16x16x32_bf16 v[52:55], v[110:113], v[102:105], v[52:55]
	v_mfma_f32_16x16x32_bf16 v[20:23], v[76:79], v[106:109], v[20:23]
	v_mfma_f32_16x16x32_bf16 v[16:19], v[110:113], v[106:109], v[16:19]
	v_mfma_f32_16x16x32_bf16 v[12:15], v[114:117], v[106:109], v[12:15]
	v_mfma_f32_16x16x32_bf16 v[8:11], v[118:121], v[106:109], v[8:11]
	v_mfma_f32_16x16x32_bf16 v[4:7], v[122:125], v[106:109], v[4:7]
	v_mfma_f32_16x16x32_bf16 v[0:3], v[126:129], v[106:109], v[0:3]
	v_mfma_f32_16x16x32_bf16 v[102:105], v[130:133], v[106:109], v[36:39]
	s_nop 2
	v_add3_u32 v36, s44, v91, v90
	ds_read_b128 v[76:79], v80 offset:18432
	ds_read_b128 v[106:109], v36
	ds_read_b128 v[110:113], v36 offset:2048
	ds_read_b128 v[130:133], v80 offset:28672
	ds_read_b128 v[134:137], v80 offset:30720
	ds_read_b128 v[114:117], v80 offset:20480
	ds_read_b128 v[118:121], v80 offset:22528
	ds_read_b128 v[122:125], v80 offset:24576
	ds_read_b128 v[126:129], v80 offset:26624
	s_waitcnt lgkmcnt(7)
	v_mfma_f32_16x16x32_bf16 v[60:63], v[72:75], v[106:109], v[60:63]
	s_waitcnt lgkmcnt(5)
	v_mfma_f32_16x16x32_bf16 v[36:39], v[130:133], v[106:109], v[32:35]
	s_waitcnt lgkmcnt(4)
	v_mfma_f32_16x16x32_bf16 v[32:35], v[134:137], v[106:109], v[28:31]
	v_mfma_f32_16x16x32_bf16 v[28:31], v[72:75], v[110:113], v[24:27]
	v_add_u32_e32 v72, s42, v85
	v_mul_hi_i32 v73, v72, s36
	v_mfma_f32_16x16x32_bf16 v[24:27], v[76:79], v[110:113], v[20:23]
	s_waitcnt lgkmcnt(3)
	v_mfma_f32_16x16x32_bf16 v[20:23], v[114:117], v[110:113], v[16:19]
	s_waitcnt lgkmcnt(2)
	v_mfma_f32_16x16x32_bf16 v[16:19], v[118:121], v[110:113], v[12:15]
	s_waitcnt lgkmcnt(1)
	v_mfma_f32_16x16x32_bf16 v[12:15], v[122:125], v[110:113], v[8:11]
	s_waitcnt lgkmcnt(0)
	v_mfma_f32_16x16x32_bf16 v[8:11], v[126:129], v[110:113], v[4:7]
	s_nop 2
	v_lshrrev_b32_e32 v4, 31, v73
	v_ashrrev_i32_e32 v5, 11, v73
	v_mfma_f32_16x16x32_bf16 v[56:59], v[76:79], v[106:109], v[56:59]
	v_add_u32_e32 v73, v5, v4
	v_mad_i32_i24 v78, v73, s37, v72
	v_lshlrev_b32_e32 v75, 13, v73
	v_mfma_f32_16x16x32_bf16 v[52:55], v[114:117], v[106:109], v[52:55]
	v_cmp_lt_i32_e32 vcc, s38, v78
	v_add3_u32 v74, v75, v78, s39
	v_mfma_f32_16x16x32_bf16 v[48:51], v[118:121], v[106:109], v[48:51]
	v_mfma_f32_16x16x32_bf16 v[44:47], v[122:125], v[106:109], v[44:47]
	v_mfma_f32_16x16x32_bf16 v[40:43], v[126:129], v[106:109], v[40:43]
	v_mfma_f32_16x16x32_bf16 v[4:7], v[130:133], v[110:113], v[0:3]
	v_mfma_f32_16x16x32_bf16 v[0:3], v[134:137], v[110:113], v[102:105]
	s_and_saveexec_b64 s[34:35], vcc
	s_xor_b64 s[34:35], exec, s[34:35]
	v_add3_u32 v72, v75, v78, s39
	s_or_saveexec_b64 s[34:35], s[34:35]
	v_mov_b64_e32 v[76:77], s[92:93]
	v_lshl_add_u32 v75, v73, 8, v78
	s_xor_b64 exec, exec, s[34:35]
	v_lshl_add_u32 v72, v73, 8, v78
	v_mov_b64_e32 v[76:77], s[6:7]
	s_or_b64 exec, exec, s[34:35]
	s_and_saveexec_b64 s[34:35], vcc
	s_xor_b64 s[34:35], exec, s[34:35]
	s_cbranch_execz .LBB0_1078
	v_mul_hi_i32_i24_e32 v79, 0x6000, v73
	v_mul_i32_i24_e32 v78, 0x6000, v73
	s_or_saveexec_b64 s[34:35], s[34:35]
	v_mov_b64_e32 v[80:81], s[92:93]
	s_xor_b64 exec, exec, s[34:35]
	s_cbranch_execnz .LBB0_1079
	s_branch .LBB0_1080

.LBB0_1091:
	s_add_i32 s48, s47, 0x8000
	s_and_b32 s8, s47, 0x8000
	s_and_b32 s47, s48, 0x8000
	s_add_i32 s49, s8, 0
	s_add_i32 s8, s47, 0
	v_add_u32_e32 v112, s8, v88
	v_lshl_add_u64 v[68:69], v[66:67], 0, s[36:37]
	v_readfirstlane_b32 s47, v112
	v_add_u32_e32 v113, 0x4000, v112
	v_lshl_add_u64 v[70:71], v[64:65], 0, s[36:37]
	v_lshl_add_u64 v[100:101], v[68:69], 0, s[16:17]
	v_add_u32_e32 v114, 0x1000, v112
	v_readfirstlane_b32 s50, v113
	s_mov_b32 m0, s47
	s_waitcnt vmcnt(0) lgkmcnt(0)
	s_barrier
	v_lshl_add_u64 v[102:103], v[70:71], 0, s[18:19]
	v_add_u32_e32 v115, 0x5000, v112
	v_readfirstlane_b32 s51, v114
	global_load_lds_dwordx4 v[100:101], off
	s_mov_b32 m0, s50
	v_lshl_add_u64 v[104:105], v[68:69], 0, s[20:21]
	v_add_u32_e32 v116, 0x2000, v112
	v_readfirstlane_b32 s52, v115
	global_load_lds_dwordx4 v[102:103], off
	s_mov_b32 m0, s51
	v_lshl_add_u64 v[106:107], v[70:71], 0, s[22:23]
	v_add_u32_e32 v117, 0x6000, v112
	v_readfirstlane_b32 s53, v116
	global_load_lds_dwordx4 v[104:105], off
	s_mov_b32 m0, s52
	v_lshl_add_u64 v[108:109], v[68:69], 0, s[24:25]
	v_add_u32_e32 v118, 0x3000, v112
	v_readfirstlane_b32 s54, v117
	global_load_lds_dwordx4 v[106:107], off
	s_mov_b32 m0, s53
	v_lshl_add_u64 v[110:111], v[70:71], 0, s[26:27]
	v_add_u32_e32 v112, 0x7000, v112
	v_readfirstlane_b32 s55, v118
	global_load_lds_dwordx4 v[108:109], off
	s_mov_b32 m0, s54
	v_lshl_add_u64 v[68:69], v[68:69], 0, s[28:29]
	v_readfirstlane_b32 s56, v112
	global_load_lds_dwordx4 v[110:111], off
	s_mov_b32 m0, s55
	v_lshl_add_u64 v[70:71], v[70:71], 0, s[30:31]
	global_load_lds_dwordx4 v[68:69], off
	s_mov_b32 m0, s56
	v_add_u32_e32 v72, s49, v84
	global_load_lds_dwordx4 v[70:71], off
	v_add_u32_e32 v169, v72, v87
	v_add3_u32 v210, s49, v87, v89
	v_add_u32_e32 v211, v72, v90
	v_add3_u32 v212, s49, v89, v90
	ds_read_b128 v[104:107], v210
	ds_read_b128 v[68:71], v169 offset:16384
	ds_read_b128 v[100:103], v169 offset:18432
	ds_read_b128 v[108:111], v210 offset:2048
	ds_read_b128 v[112:115], v169 offset:20480
	ds_read_b128 v[116:119], v169 offset:22528
	ds_read_b128 v[120:123], v169 offset:24576
	ds_read_b128 v[124:127], v169 offset:26624
	ds_read_b128 v[128:131], v169 offset:28672
	ds_read_b128 v[132:135], v169 offset:30720
	ds_read_b128 v[178:181], v212
	ds_read_b128 v[170:173], v211 offset:16384
	ds_read_b128 v[174:177], v211 offset:18432
	ds_read_b128 v[182:185], v212 offset:2048
	ds_read_b128 v[186:189], v211 offset:20480
	ds_read_b128 v[190:193], v211 offset:22528
	ds_read_b128 v[194:197], v211 offset:24576
	ds_read_b128 v[198:201], v211 offset:26624
	ds_read_b128 v[202:205], v211 offset:28672
	ds_read_b128 v[206:209], v211 offset:30720
	s_add_u32 s36, s36, 0x80
	s_addc_u32 s37, s37, 0
	s_cmpk_eq_i32 s36, 0x780
	s_mov_b32 s47, s48
	s_waitcnt lgkmcnt(15)
	v_mfma_f32_16x16x32_bf16 v[60:63], v[68:71], v[104:107], v[60:63]
	v_mfma_f32_16x16x32_bf16 v[56:59], v[100:103], v[104:107], v[56:59]
	v_mfma_f32_16x16x32_bf16 v[28:31], v[68:71], v[108:111], v[28:31]
	v_mfma_f32_16x16x32_bf16 v[24:27], v[100:103], v[108:111], v[24:27]
	v_mfma_f32_16x16x32_bf16 v[52:55], v[112:115], v[104:107], v[52:55]
	v_mfma_f32_16x16x32_bf16 v[16:19], v[112:115], v[108:111], v[16:19]
	s_waitcnt lgkmcnt(14)
	v_mfma_f32_16x16x32_bf16 v[48:51], v[116:119], v[104:107], v[48:51]
	v_mfma_f32_16x16x32_bf16 v[12:15], v[116:119], v[108:111], v[12:15]
	s_waitcnt lgkmcnt(13)
	v_mfma_f32_16x16x32_bf16 v[44:47], v[120:123], v[104:107], v[44:47]
	v_mfma_f32_16x16x32_bf16 v[8:11], v[120:123], v[108:111], v[8:11]
	s_waitcnt lgkmcnt(12)
	v_mfma_f32_16x16x32_bf16 v[40:43], v[124:127], v[104:107], v[40:43]
	v_mfma_f32_16x16x32_bf16 v[4:7], v[124:127], v[108:111], v[4:7]
	s_waitcnt lgkmcnt(11)
	v_mfma_f32_16x16x32_bf16 v[36:39], v[128:131], v[104:107], v[36:39]
	v_mfma_f32_16x16x32_bf16 v[0:3], v[128:131], v[108:111], v[0:3]
	s_waitcnt lgkmcnt(10)
	v_mfma_f32_16x16x32_bf16 v[32:35], v[132:135], v[104:107], v[32:35]
	v_mfma_f32_16x16x32_bf16 v[20:23], v[132:135], v[108:111], v[20:23]
	s_waitcnt lgkmcnt(8)
	v_mfma_f32_16x16x32_bf16 v[60:63], v[170:173], v[178:181], v[60:63]
	s_waitcnt lgkmcnt(7)
	v_mfma_f32_16x16x32_bf16 v[56:59], v[174:177], v[178:181], v[56:59]
	s_waitcnt lgkmcnt(6)
	v_mfma_f32_16x16x32_bf16 v[28:31], v[170:173], v[182:185], v[28:31]
	v_mfma_f32_16x16x32_bf16 v[24:27], v[174:177], v[182:185], v[24:27]
	s_waitcnt lgkmcnt(5)
	v_mfma_f32_16x16x32_bf16 v[52:55], v[186:189], v[178:181], v[52:55]
	v_mfma_f32_16x16x32_bf16 v[16:19], v[186:189], v[182:185], v[16:19]
	s_waitcnt lgkmcnt(4)
	v_mfma_f32_16x16x32_bf16 v[48:51], v[190:193], v[178:181], v[48:51]
	v_mfma_f32_16x16x32_bf16 v[12:15], v[190:193], v[182:185], v[12:15]
	s_waitcnt lgkmcnt(3)
	v_mfma_f32_16x16x32_bf16 v[44:47], v[194:197], v[178:181], v[44:47]
	v_mfma_f32_16x16x32_bf16 v[8:11], v[194:197], v[182:185], v[8:11]
	s_waitcnt lgkmcnt(2)
	v_mfma_f32_16x16x32_bf16 v[40:43], v[198:201], v[178:181], v[40:43]
	v_mfma_f32_16x16x32_bf16 v[4:7], v[198:201], v[182:185], v[4:7]
	s_waitcnt lgkmcnt(1)
	v_mfma_f32_16x16x32_bf16 v[36:39], v[202:205], v[178:181], v[36:39]
	v_mfma_f32_16x16x32_bf16 v[0:3], v[202:205], v[182:185], v[0:3]
	s_waitcnt lgkmcnt(0)
	v_mfma_f32_16x16x32_bf16 v[32:35], v[206:209], v[178:181], v[32:35]
	v_mfma_f32_16x16x32_bf16 v[20:23], v[206:209], v[182:185], v[20:23]
	s_cbranch_scc0 .LBB0_1091
	v_lshl_add_u32 v99, s46, 7, v85
	v_mul_hi_i32 v64, v99, s39
	v_lshrrev_b32_e32 v65, 31, v64
	v_ashrrev_i32_e32 v64, 11, v64
	v_add_u32_e32 v64, v64, v65
	v_mad_i32_i24 v65, v64, s40, v99
	v_cmp_lt_i32_e32 vcc, s41, v65
	v_lshl_or_b32 v72, s45, 9, v86
	s_waitcnt vmcnt(0)
	v_cndmask_b32_e32 v64, 2, v64, vcc
	v_mul_hi_i32_i24_e32 v65, 0x6000, v64
	v_mul_i32_i24_e32 v64, 0x6000, v64
	v_lshl_add_u64 v[64:65], s[94:95], 0, v[64:65]
	v_lshl_add_u64 v[150:151], v[64:65], 0, s[34:35]
	v_lshl_add_u64 v[64:65], v[150:151], 0, v[72:73]
	s_barrier
	global_load_dwordx4 v[100:103], v[64:65], off
	v_add3_u32 v64, s8, v87, v89
	v_add_u32_e32 v68, s8, v84
	ds_read_b128 v[104:107], v64
	ds_read_b128 v[108:111], v64 offset:2048
	v_add3_u32 v65, s8, v90, v89
	v_add_u32_e32 v145, v68, v87
	ds_read_b128 v[112:115], v65
	ds_read_b128 v[64:67], v65 offset:2048
	v_add_u32_e32 v168, v68, v90
	ds_read_b128 v[116:119], v145 offset:16384
	ds_read_b128 v[120:123], v145 offset:18432
	ds_read_b128 v[124:127], v168 offset:16384
	ds_read_b128 v[68:71], v168 offset:18432
	v_mul_hi_i32 v128, v99, s38
	s_waitcnt lgkmcnt(3)
	v_mfma_f32_16x16x32_bf16 v[60:63], v[116:119], v[104:107], v[60:63]
	v_lshrrev_b32_e32 v129, 31, v128
	v_lshrrev_b32_e32 v128, 11, v128
	v_add_u32_e32 v128, v128, v129
	v_lshl_add_u32 v128, v128, 13, v99
	s_lshl_b32 s8, s44, 9
	v_ashrrev_i32_e32 v129, 31, v128
	s_waitcnt lgkmcnt(1)
	v_mfma_f32_16x16x32_bf16 v[60:63], v[124:127], v[112:115], v[60:63]
	v_lshl_add_u64 v[128:129], v[128:129], 0, s[8:9]
	v_lshlrev_b64 v[128:129], 12, v[128:129]
	v_lshl_add_u64 v[128:129], s[6:7], 0, v[128:129]
	v_mov_b32_e32 v153, v73
	v_or_b32_e32 v152, 16, v72
	v_lshl_add_u64 v[154:155], v[128:129], 0, v[72:73]
	v_lshl_add_u64 v[128:129], v[150:151], 0, v[152:153]
	v_mfma_f32_16x16x32_bf16 v[56:59], v[120:123], v[104:107], v[56:59]
	v_mov_b32_e32 v157, v73
	v_or_b32_e32 v156, 0x80, v72
	v_mov_b32_e32 v159, v73
	s_waitcnt lgkmcnt(0)
	v_mfma_f32_16x16x32_bf16 v[56:59], v[68:71], v[112:115], v[56:59]
	v_or_b32_e32 v158, 0x90, v72
	v_lshl_add_u64 v[136:137], v[150:151], 0, v[158:159]
	v_mov_b32_e32 v161, v73
	v_or_b32_e32 v160, 0x100, v72
	v_mov_b32_e32 v163, v73
	v_or_b32_e32 v162, 0x110, v72
	v_lshl_add_u64 v[146:147], v[150:151], 0, v[162:163]
	v_mov_b32_e32 v165, v73
	v_or_b32_e32 v164, 0x180, v72
	v_lshl_add_u64 v[166:167], v[150:151], 0, v[164:165]
	v_mfma_f32_16x16x32_bf16 v[28:31], v[116:119], v[108:111], v[28:31]
	v_or_b32_e32 v99, 16, v99
	s_add_i32 s43, s43, s33
	s_add_i32 s42, s42, s33
	v_mfma_f32_16x16x32_bf16 v[28:31], v[124:127], v[64:67], v[28:31]
	s_cmpk_gt_i32 s43, 0x7f
	s_waitcnt vmcnt(0)
	v_pk_mul_f32 v[62:63], v[62:63], v[102:103]
	v_pk_mul_f32 v[60:61], v[60:61], v[100:101]
	global_store_dwordx4 v[154:155], v[60:63], off
	global_load_dwordx4 v[60:63], v[128:129], off
	v_lshl_add_u64 v[100:101], v[150:151], 0, v[156:157]
	v_mfma_f32_16x16x32_bf16 v[24:27], v[120:123], v[108:111], v[24:27]
	s_waitcnt vmcnt(0)
	v_pk_mul_f32 v[58:59], v[58:59], v[62:63]
	v_pk_mul_f32 v[56:57], v[56:57], v[60:61]
	global_store_dwordx4 v[154:155], v[56:59], off offset:16
	global_load_dwordx4 v[56:59], v[100:101], off
	ds_read_b128 v[60:63], v145 offset:20480
	ds_read_b128 v[100:103], v168 offset:20480
	s_waitcnt lgkmcnt(1)
	v_mfma_f32_16x16x32_bf16 v[52:55], v[60:63], v[104:107], v[52:55]
	ds_read_b128 v[128:131], v145 offset:22528
	ds_read_b128 v[132:135], v168 offset:22528
	s_waitcnt lgkmcnt(2)
	v_mfma_f32_16x16x32_bf16 v[52:55], v[100:103], v[112:115], v[52:55]
	s_waitcnt lgkmcnt(1)
	v_mfma_f32_16x16x32_bf16 v[48:51], v[128:131], v[104:107], v[48:51]
	s_waitcnt vmcnt(0)
	s_nop 4
	v_pk_mul_f32 v[54:55], v[54:55], v[58:59]
	v_pk_mul_f32 v[52:53], v[52:53], v[56:57]
	global_store_dwordx4 v[154:155], v[52:55], off offset:128
	global_load_dwordx4 v[52:55], v[136:137], off
	s_waitcnt lgkmcnt(0)
	v_mfma_f32_16x16x32_bf16 v[48:51], v[132:135], v[112:115], v[48:51]
	v_lshl_add_u64 v[56:57], v[150:151], 0, v[160:161]
	v_mfma_f32_16x16x32_bf16 v[24:27], v[68:71], v[64:67], v[24:27]
	v_mfma_f32_16x16x32_bf16 v[16:19], v[60:63], v[108:111], v[16:19]
	s_waitcnt vmcnt(0)
	s_nop 3
	v_pk_mul_f32 v[50:51], v[50:51], v[54:55]
	v_pk_mul_f32 v[48:49], v[48:49], v[52:53]
	global_store_dwordx4 v[154:155], v[48:51], off offset:144
	global_load_dwordx4 v[48:51], v[56:57], off
	ds_read_b128 v[52:55], v145 offset:24576
	ds_read_b128 v[56:59], v168 offset:24576
	s_waitcnt lgkmcnt(1)
	v_mfma_f32_16x16x32_bf16 v[44:47], v[52:55], v[104:107], v[44:47]
	ds_read_b128 v[136:139], v145 offset:26624
	ds_read_b128 v[140:143], v168 offset:26624
	s_waitcnt lgkmcnt(2)
	v_mfma_f32_16x16x32_bf16 v[44:47], v[56:59], v[112:115], v[44:47]
	s_waitcnt lgkmcnt(1)
	v_mfma_f32_16x16x32_bf16 v[40:43], v[136:139], v[104:107], v[40:43]
	s_waitcnt vmcnt(0)
	s_nop 4
	v_pk_mul_f32 v[46:47], v[46:47], v[50:51]
	v_pk_mul_f32 v[44:45], v[44:45], v[48:49]
	global_store_dwordx4 v[154:155], v[44:47], off offset:256
	global_load_dwordx4 v[44:47], v[146:147], off
	s_waitcnt lgkmcnt(0)
	v_mfma_f32_16x16x32_bf16 v[40:43], v[140:143], v[112:115], v[40:43]
	ds_read_b128 v[48:51], v145 offset:28672
	ds_read_b128 v[146:149], v145 offset:30720
	s_waitcnt lgkmcnt(1)
	v_mfma_f32_16x16x32_bf16 v[36:39], v[48:51], v[104:107], v[36:39]
	s_waitcnt vmcnt(0)
	s_nop 2
	v_pk_mul_f32 v[42:43], v[42:43], v[46:47]
	v_pk_mul_f32 v[40:41], v[40:41], v[44:45]
	global_store_dwordx4 v[154:155], v[40:43], off offset:272
	global_load_dwordx4 v[40:43], v[166:167], off
	ds_read_b128 v[44:47], v168 offset:28672
	s_waitcnt lgkmcnt(1)
	v_mfma_f32_16x16x32_bf16 v[32:35], v[146:149], v[104:107], v[32:35]
	ds_read_b128 v[104:107], v168 offset:30720
	v_mov_b32_e32 v167, v73
	v_or_b32_e32 v166, 0x190, v72
	s_waitcnt lgkmcnt(1)
	v_mfma_f32_16x16x32_bf16 v[36:39], v[44:47], v[112:115], v[36:39]
	v_lshl_add_u64 v[116:117], v[150:151], 0, v[166:167]
	s_waitcnt vmcnt(0)
	s_nop 5
	v_pk_mul_f32 v[38:39], v[38:39], v[42:43]
	v_pk_mul_f32 v[36:37], v[36:37], v[40:41]
	global_store_dwordx4 v[154:155], v[36:39], off offset:384
	global_load_dwordx4 v[36:39], v[116:117], off
	v_mul_hi_i32 v40, v99, s39
	v_lshrrev_b32_e32 v41, 31, v40
	v_ashrrev_i32_e32 v40, 11, v40
	v_add_u32_e32 v40, v40, v41
	v_mad_i32_i24 v41, v40, s40, v99
	v_cmp_lt_i32_e32 vcc, s41, v41
	s_waitcnt lgkmcnt(0)
	v_mfma_f32_16x16x32_bf16 v[32:35], v[104:107], v[112:115], v[32:35]
	v_cndmask_b32_e32 v40, 2, v40, vcc
	v_mul_hi_i32_i24_e32 v41, 0x6000, v40
	v_mul_i32_i24_e32 v40, 0x6000, v40
	v_lshl_add_u64 v[40:41], s[94:95], 0, v[40:41]
	v_lshl_add_u64 v[40:41], v[40:41], 0, s[34:35]
	v_lshl_add_u64 v[42:43], v[40:41], 0, v[72:73]
	v_mfma_f32_16x16x32_bf16 v[16:19], v[100:103], v[64:67], v[16:19]
	s_waitcnt vmcnt(0)
	v_pk_mul_f32 v[34:35], v[34:35], v[38:39]
	v_pk_mul_f32 v[32:33], v[32:33], v[36:37]
	global_store_dwordx4 v[154:155], v[32:35], off offset:400
	global_load_dwordx4 v[32:35], v[42:43], off
	v_mul_hi_i32 v36, v99, s38
	v_lshrrev_b32_e32 v37, 31, v36
	v_lshrrev_b32_e32 v36, 11, v36
	v_add_u32_e32 v36, v36, v37
	v_lshl_add_u32 v36, v36, 13, v99
	v_ashrrev_i32_e32 v37, 31, v36
	v_lshl_add_u64 v[36:37], v[36:37], 0, s[8:9]
	v_lshlrev_b64 v[36:37], 12, v[36:37]
	v_lshl_add_u64 v[36:37], s[6:7], 0, v[36:37]
	v_lshl_add_u64 v[36:37], v[36:37], 0, v[72:73]
	v_lshl_add_u64 v[38:39], v[40:41], 0, v[152:153]
	v_mfma_f32_16x16x32_bf16 v[12:15], v[128:131], v[108:111], v[12:15]
	s_waitcnt vmcnt(0)
	v_pk_mul_f32 v[30:31], v[30:31], v[34:35]
	v_pk_mul_f32 v[28:29], v[28:29], v[32:33]
	global_store_dwordx4 v[36:37], v[28:31], off
	global_load_dwordx4 v[28:31], v[38:39], off
	v_lshl_add_u64 v[32:33], v[40:41], 0, v[156:157]
	v_mfma_f32_16x16x32_bf16 v[12:15], v[132:135], v[64:67], v[12:15]
	s_waitcnt vmcnt(0)
	v_pk_mul_f32 v[26:27], v[26:27], v[30:31]
	v_pk_mul_f32 v[24:25], v[24:25], v[28:29]
	global_store_dwordx4 v[36:37], v[24:27], off offset:16
	global_load_dwordx4 v[24:27], v[32:33], off
	v_lshl_add_u64 v[28:29], v[40:41], 0, v[158:159]
	v_mfma_f32_16x16x32_bf16 v[8:11], v[52:55], v[108:111], v[8:11]
	s_waitcnt vmcnt(0)
	v_pk_mul_f32 v[18:19], v[18:19], v[26:27]
	v_pk_mul_f32 v[16:17], v[16:17], v[24:25]
	global_store_dwordx4 v[36:37], v[16:19], off offset:128
	global_load_dwordx4 v[16:19], v[28:29], off
	v_lshl_add_u64 v[24:25], v[40:41], 0, v[160:161]
	v_mfma_f32_16x16x32_bf16 v[8:11], v[56:59], v[64:67], v[8:11]
	s_waitcnt vmcnt(0)
	v_pk_mul_f32 v[14:15], v[14:15], v[18:19]
	v_pk_mul_f32 v[12:13], v[12:13], v[16:17]
	global_store_dwordx4 v[36:37], v[12:15], off offset:144
	global_load_dwordx4 v[12:15], v[24:25], off
	v_lshl_add_u64 v[16:17], v[40:41], 0, v[162:163]
	v_mfma_f32_16x16x32_bf16 v[4:7], v[136:139], v[108:111], v[4:7]
	s_waitcnt vmcnt(0)
	v_pk_mul_f32 v[10:11], v[10:11], v[14:15]
	v_pk_mul_f32 v[8:9], v[8:9], v[12:13]
	global_store_dwordx4 v[36:37], v[8:11], off offset:256
	global_load_dwordx4 v[8:11], v[16:17], off
	v_mfma_f32_16x16x32_bf16 v[4:7], v[140:143], v[64:67], v[4:7]
	v_lshl_add_u64 v[12:13], v[40:41], 0, v[164:165]
	v_mfma_f32_16x16x32_bf16 v[0:3], v[48:51], v[108:111], v[0:3]
	v_mfma_f32_16x16x32_bf16 v[0:3], v[44:47], v[64:67], v[0:3]
	s_waitcnt vmcnt(0)
	s_nop 3
	v_pk_mul_f32 v[6:7], v[6:7], v[10:11]
	v_pk_mul_f32 v[4:5], v[4:5], v[8:9]
	global_store_dwordx4 v[36:37], v[4:7], off offset:272
	global_load_dwordx4 v[4:7], v[12:13], off
	v_lshl_add_u64 v[8:9], v[40:41], 0, v[166:167]
	v_mfma_f32_16x16x32_bf16 v[20:23], v[146:149], v[108:111], v[20:23]
	s_waitcnt vmcnt(0)
	v_pk_mul_f32 v[2:3], v[2:3], v[6:7]
	v_pk_mul_f32 v[0:1], v[0:1], v[4:5]
	global_store_dwordx4 v[36:37], v[0:3], off offset:384
	global_load_dwordx4 v[0:3], v[8:9], off
	v_mfma_f32_16x16x32_bf16 v[4:7], v[104:107], v[64:67], v[20:23]
	s_waitcnt vmcnt(0)
	s_nop 6
	v_pk_mul_f32 v[2:3], v[6:7], v[2:3]
	v_pk_mul_f32 v[0:1], v[4:5], v[0:1]
	global_store_dwordx4 v[36:37], v[0:3], off offset:400
	s_cbranch_scc0 .LBB0_1090

.LBB0_1217:
	s_add_i32 s41, s3, 0x8000
	s_and_b32 s40, s41, 0x8000
	s_add_i32 s40, s40, 0
	v_add_u32_e32 v120, s40, v86
	v_lshl_add_u64 v[104:105], v[82:83], 0, s[0:1]
	v_readfirstlane_b32 s42, v120
	v_add_u32_e32 v121, 0x4000, v120
	v_lshl_add_u64 v[106:107], v[84:85], 0, s[0:1]
	v_lshl_add_u64 v[108:109], v[104:105], 0, s[18:19]
	v_add_u32_e32 v122, 0x1000, v120
	v_readfirstlane_b32 s43, v121
	s_mov_b32 m0, s42
	s_waitcnt vmcnt(0) lgkmcnt(0)
	s_barrier
	v_lshl_add_u64 v[110:111], v[106:107], 0, s[20:21]
	v_add_u32_e32 v123, 0x5000, v120
	v_readfirstlane_b32 s44, v122
	global_load_lds_dwordx4 v[108:109], off
	s_mov_b32 m0, s43
	v_lshl_add_u64 v[112:113], v[104:105], 0, s[22:23]
	v_add_u32_e32 v124, 0x2000, v120
	v_readfirstlane_b32 s45, v123
	global_load_lds_dwordx4 v[110:111], off
	s_mov_b32 m0, s44
	v_lshl_add_u64 v[114:115], v[106:107], 0, s[24:25]
	v_add_u32_e32 v125, 0x6000, v120
	v_readfirstlane_b32 s53, v124
	global_load_lds_dwordx4 v[112:113], off
	s_mov_b32 m0, s45
	v_lshl_add_u64 v[116:117], v[104:105], 0, s[26:27]
	v_add_u32_e32 v126, 0x3000, v120
	v_readfirstlane_b32 s54, v125
	global_load_lds_dwordx4 v[114:115], off
	s_mov_b32 m0, s53
	v_lshl_add_u64 v[118:119], v[106:107], 0, s[28:29]
	v_add_u32_e32 v120, 0x7000, v120
	v_readfirstlane_b32 s55, v126
	global_load_lds_dwordx4 v[116:117], off
	s_mov_b32 m0, s54
	v_lshl_add_u64 v[104:105], v[104:105], 0, s[30:31]
	v_readfirstlane_b32 s56, v120
	global_load_lds_dwordx4 v[118:119], off
	s_mov_b32 m0, s55
	v_lshl_add_u64 v[106:107], v[106:107], 0, s[34:35]
	global_load_lds_dwordx4 v[104:105], off
	s_mov_b32 m0, s56
	s_and_b32 s3, s3, 0x8000
	global_load_lds_dwordx4 v[106:107], off
	s_add_i32 s3, s3, 0
	v_add3_u32 v145, s3, v87, v88
	v_add3_u32 v186, s3, v88, v89
	v_add3_u32 v187, s3, v87, v90
	v_add3_u32 v188, s3, v89, v90
	ds_read_b128 v[112:115], v186
	ds_read_b128 v[104:107], v145 offset:16384
	ds_read_b128 v[108:111], v145 offset:18432
	ds_read_b128 v[116:119], v186 offset:2048
	ds_read_b128 v[120:123], v145 offset:20480
	ds_read_b128 v[124:127], v145 offset:22528
	ds_read_b128 v[128:131], v145 offset:24576
	ds_read_b128 v[132:135], v145 offset:26624
	ds_read_b128 v[136:139], v145 offset:28672
	ds_read_b128 v[140:143], v145 offset:30720
	ds_read_b128 v[154:157], v188
	ds_read_b128 v[146:149], v187 offset:16384
	ds_read_b128 v[150:153], v187 offset:18432
	ds_read_b128 v[158:161], v188 offset:2048
	ds_read_b128 v[162:165], v187 offset:20480
	ds_read_b128 v[166:169], v187 offset:22528
	ds_read_b128 v[170:173], v187 offset:24576
	ds_read_b128 v[174:177], v187 offset:26624
	ds_read_b128 v[178:181], v187 offset:28672
	ds_read_b128 v[182:185], v187 offset:30720
	s_add_u32 s0, s0, 0x80
	s_addc_u32 s1, s1, 0
	s_cmpk_eq_i32 s0, 0x780
	s_mov_b32 s3, s41
	s_waitcnt lgkmcnt(15)
	v_mfma_f32_16x16x32_bf16 v[60:63], v[104:107], v[112:115], v[60:63]
	v_mfma_f32_16x16x32_bf16 v[56:59], v[108:111], v[112:115], v[56:59]
	v_mfma_f32_16x16x32_bf16 v[24:27], v[104:107], v[116:119], v[24:27]
	v_mfma_f32_16x16x32_bf16 v[20:23], v[108:111], v[116:119], v[20:23]
	v_mfma_f32_16x16x32_bf16 v[52:55], v[120:123], v[112:115], v[52:55]
	v_mfma_f32_16x16x32_bf16 v[16:19], v[120:123], v[116:119], v[16:19]
	s_waitcnt lgkmcnt(14)
	v_mfma_f32_16x16x32_bf16 v[48:51], v[124:127], v[112:115], v[48:51]
	v_mfma_f32_16x16x32_bf16 v[12:15], v[124:127], v[116:119], v[12:15]
	s_waitcnt lgkmcnt(13)
	v_mfma_f32_16x16x32_bf16 v[44:47], v[128:131], v[112:115], v[44:47]
	v_mfma_f32_16x16x32_bf16 v[8:11], v[128:131], v[116:119], v[8:11]
	s_waitcnt lgkmcnt(12)
	v_mfma_f32_16x16x32_bf16 v[36:39], v[132:135], v[112:115], v[36:39]
	v_mfma_f32_16x16x32_bf16 v[4:7], v[132:135], v[116:119], v[4:7]
	s_waitcnt lgkmcnt(11)
	v_mfma_f32_16x16x32_bf16 v[32:35], v[136:139], v[112:115], v[32:35]
	v_mfma_f32_16x16x32_bf16 v[0:3], v[136:139], v[116:119], v[0:3]
	s_waitcnt lgkmcnt(10)
	v_mfma_f32_16x16x32_bf16 v[28:31], v[140:143], v[112:115], v[28:31]
	v_mfma_f32_16x16x32_bf16 v[40:43], v[140:143], v[116:119], v[40:43]
	s_waitcnt lgkmcnt(8)
	v_mfma_f32_16x16x32_bf16 v[60:63], v[146:149], v[154:157], v[60:63]
	s_waitcnt lgkmcnt(7)
	v_mfma_f32_16x16x32_bf16 v[56:59], v[150:153], v[154:157], v[56:59]
	s_waitcnt lgkmcnt(6)
	v_mfma_f32_16x16x32_bf16 v[24:27], v[146:149], v[158:161], v[24:27]
	v_mfma_f32_16x16x32_bf16 v[20:23], v[150:153], v[158:161], v[20:23]
	s_waitcnt lgkmcnt(5)
	v_mfma_f32_16x16x32_bf16 v[52:55], v[162:165], v[154:157], v[52:55]
	v_mfma_f32_16x16x32_bf16 v[16:19], v[162:165], v[158:161], v[16:19]
	s_waitcnt lgkmcnt(4)
	v_mfma_f32_16x16x32_bf16 v[48:51], v[166:169], v[154:157], v[48:51]
	v_mfma_f32_16x16x32_bf16 v[12:15], v[166:169], v[158:161], v[12:15]
	s_waitcnt lgkmcnt(3)
	v_mfma_f32_16x16x32_bf16 v[44:47], v[170:173], v[154:157], v[44:47]
	v_mfma_f32_16x16x32_bf16 v[8:11], v[170:173], v[158:161], v[8:11]
	s_waitcnt lgkmcnt(2)
	v_mfma_f32_16x16x32_bf16 v[36:39], v[174:177], v[154:157], v[36:39]
	v_mfma_f32_16x16x32_bf16 v[4:7], v[174:177], v[158:161], v[4:7]
	s_waitcnt lgkmcnt(1)
	v_mfma_f32_16x16x32_bf16 v[32:35], v[178:181], v[154:157], v[32:35]
	v_mfma_f32_16x16x32_bf16 v[0:3], v[178:181], v[158:161], v[0:3]
	s_waitcnt lgkmcnt(0)
	v_mfma_f32_16x16x32_bf16 v[28:31], v[182:185], v[154:157], v[28:31]
	v_mfma_f32_16x16x32_bf16 v[40:43], v[182:185], v[158:161], v[40:43]
	s_cbranch_scc0 .LBB0_1217
	v_add_u32_e32 v64, s40, v87
	v_add_u32_e32 v103, v64, v88
	v_add3_u32 v112, s40, v88, v89
	s_waitcnt vmcnt(0)
	s_barrier
	ds_read_b128 v[82:85], v103 offset:16384
	ds_read_b128 v[104:107], v103 offset:18432
	ds_read_b128 v[108:111], v112
	ds_read_b128 v[112:115], v112 offset:2048
	ds_read_b128 v[116:119], v103 offset:20480
	ds_read_b128 v[120:123], v103 offset:22528
	ds_read_b128 v[124:127], v103 offset:24576
	ds_read_b128 v[128:131], v103 offset:26624
	ds_read_b128 v[132:135], v103 offset:28672
	ds_read_b128 v[136:139], v103 offset:30720
	v_add_u32_e32 v64, v64, v90
	s_waitcnt lgkmcnt(7)
	v_mfma_f32_16x16x32_bf16 v[60:63], v[82:85], v[108:111], v[60:63]
	s_mul_hi_i32 s0, s2, 0x3e0f83e1
	s_lshr_b32 s1, s0, 31
	s_ashr_i32 s56, s0, 4
	v_mfma_f32_16x16x32_bf16 v[56:59], v[104:107], v[108:111], v[56:59]
	s_add_i32 s56, s56, s1
	s_cmp_gt_i32 s39, 11
	s_cselect_b64 s[0:1], -1, 0
	s_waitcnt lgkmcnt(4)
	v_mfma_f32_16x16x32_bf16 v[48:51], v[120:123], v[108:111], v[48:51]
	s_lshl_b32 s53, s2, 7
	s_cmp_lt_i32 s39, 12
	s_mul_i32 s54, s56, 0xffffdf00
	s_waitcnt lgkmcnt(3)
	v_mfma_f32_16x16x32_bf16 v[44:47], v[124:127], v[108:111], v[44:47]
	s_waitcnt lgkmcnt(2)
	v_mfma_f32_16x16x32_bf16 v[36:39], v[128:131], v[108:111], v[36:39]
	s_waitcnt lgkmcnt(1)
	v_mfma_f32_16x16x32_bf16 v[32:35], v[132:135], v[108:111], v[32:35]
	s_waitcnt lgkmcnt(0)
	v_mfma_f32_16x16x32_bf16 v[28:31], v[136:139], v[108:111], v[28:31]
	v_mfma_f32_16x16x32_bf16 v[24:27], v[82:85], v[112:115], v[24:27]
	ds_read_b128 v[82:85], v64 offset:16384
	v_mfma_f32_16x16x32_bf16 v[52:55], v[116:119], v[108:111], v[52:55]
	v_mfma_f32_16x16x32_bf16 v[20:23], v[104:107], v[112:115], v[20:23]
	v_mfma_f32_16x16x32_bf16 v[16:19], v[116:119], v[112:115], v[16:19]
	v_mfma_f32_16x16x32_bf16 v[12:15], v[120:123], v[112:115], v[12:15]
	v_mfma_f32_16x16x32_bf16 v[8:11], v[124:127], v[112:115], v[8:11]
	v_mfma_f32_16x16x32_bf16 v[4:7], v[128:131], v[112:115], v[4:7]
	v_mfma_f32_16x16x32_bf16 v[0:3], v[132:135], v[112:115], v[0:3]
	v_mfma_f32_16x16x32_bf16 v[104:107], v[136:139], v[112:115], v[40:43]
	s_nop 2
	v_add3_u32 v40, s40, v90, v89
	ds_read_b128 v[108:111], v64 offset:18432
	ds_read_b128 v[112:115], v40
	ds_read_b128 v[116:119], v40 offset:2048
	ds_read_b128 v[120:123], v64 offset:20480
	ds_read_b128 v[124:127], v64 offset:22528
	ds_read_b128 v[128:131], v64 offset:24576
	ds_read_b128 v[132:135], v64 offset:26624
	ds_read_b128 v[136:139], v64 offset:28672
	ds_read_b128 v[140:143], v64 offset:30720
	s_waitcnt lgkmcnt(7)
	v_mfma_f32_16x16x32_bf16 v[60:63], v[82:85], v[112:115], v[60:63]
	v_mfma_f32_16x16x32_bf16 v[56:59], v[108:111], v[112:115], v[56:59]
	s_waitcnt lgkmcnt(5)
	v_mfma_f32_16x16x32_bf16 v[52:55], v[120:123], v[112:115], v[52:55]
	s_waitcnt lgkmcnt(4)
	v_mfma_f32_16x16x32_bf16 v[48:51], v[124:127], v[112:115], v[48:51]
	s_waitcnt lgkmcnt(3)
	v_mfma_f32_16x16x32_bf16 v[44:47], v[128:131], v[112:115], v[44:47]
	s_waitcnt lgkmcnt(2)
	v_mfma_f32_16x16x32_bf16 v[40:43], v[132:135], v[112:115], v[36:39]
	s_waitcnt lgkmcnt(1)
	v_mfma_f32_16x16x32_bf16 v[36:39], v[136:139], v[112:115], v[32:35]
	s_waitcnt lgkmcnt(0)
	v_mfma_f32_16x16x32_bf16 v[32:35], v[140:143], v[112:115], v[28:31]
	v_mfma_f32_16x16x32_bf16 v[28:31], v[82:85], v[116:119], v[24:27]
	v_mfma_f32_16x16x32_bf16 v[24:27], v[108:111], v[116:119], v[20:23]
	v_mfma_f32_16x16x32_bf16 v[20:23], v[120:123], v[116:119], v[16:19]
	v_mfma_f32_16x16x32_bf16 v[16:19], v[124:127], v[116:119], v[12:15]
	v_mfma_f32_16x16x32_bf16 v[12:15], v[128:131], v[116:119], v[8:11]
	v_mfma_f32_16x16x32_bf16 v[8:11], v[132:135], v[116:119], v[4:7]
	v_mfma_f32_16x16x32_bf16 v[4:7], v[136:139], v[116:119], v[0:3]
	v_mfma_f32_16x16x32_bf16 v[0:3], v[140:143], v[116:119], v[104:107]
	s_cbranch_scc0 .LBB0_1224
	s_add_i32 s40, s54, s53
	v_add_u32_e32 v64, s40, v70
	v_cmp_lt_i32_e32 vcc, s48, v64
	s_and_saveexec_b64 s[2:3], vcc
	s_cbranch_execz .LBB0_1221
	v_lshl_add_u32 v64, v64, 5, v102
	v_lshlrev_b64 v[108:109], 2, v[64:65]
	v_lshl_add_u64 v[104:105], v[76:77], 0, v[108:109]
	global_load_dwordx4 v[82:85], v[104:105], off
	s_nop 0
	global_load_dwordx4 v[104:107], v[104:105], off offset:16
	v_lshl_add_u64 v[112:113], v[74:75], 0, v[108:109]
	global_load_dwordx4 v[108:111], v[112:113], off
	s_nop 0
	global_load_dwordx4 v[112:115], v[112:113], off offset:16
	s_waitcnt vmcnt(3)
	v_pk_mul_f32 v[116:117], v[54:55], v[84:85]
	v_pk_mul_f32 v[118:119], v[52:53], v[82:83]
	v_pk_mul_f32 v[120:121], v[62:63], v[84:85]
	v_pk_mul_f32 v[122:123], v[60:61], v[82:83]
	s_waitcnt vmcnt(2)
	v_pk_mul_f32 v[124:125], v[50:51], v[106:107]
	v_pk_mul_f32 v[126:127], v[48:49], v[104:105]
	v_pk_mul_f32 v[128:129], v[58:59], v[106:107]
	v_pk_mul_f32 v[130:131], v[56:57], v[104:105]
	v_pk_mul_f32 v[132:133], v[38:39], v[84:85]
	v_pk_mul_f32 v[134:135], v[36:37], v[82:83]
	v_pk_mul_f32 v[84:85], v[46:47], v[84:85]
	v_pk_mul_f32 v[82:83], v[44:45], v[82:83]
	v_pk_mul_f32 v[136:137], v[34:35], v[106:107]
	v_pk_mul_f32 v[138:139], v[32:33], v[104:105]
	v_pk_mul_f32 v[106:107], v[42:43], v[106:107]
	v_pk_mul_f32 v[104:105], v[40:41], v[104:105]
	s_waitcnt vmcnt(1)
	v_pk_fma_f32 v[62:63], v[62:63], v[110:111], v[116:117] neg_lo:[0,0,1] neg_hi:[0,0,1]
	v_pk_fma_f32 v[60:61], v[60:61], v[108:109], v[118:119] neg_lo:[0,0,1] neg_hi:[0,0,1]
	v_pk_fma_f32 v[54:55], v[54:55], v[110:111], v[120:121]
	v_pk_fma_f32 v[52:53], v[52:53], v[108:109], v[122:123]
	s_waitcnt vmcnt(0)
	v_pk_fma_f32 v[58:59], v[58:59], v[114:115], v[124:125] neg_lo:[0,0,1] neg_hi:[0,0,1]
	v_pk_fma_f32 v[56:57], v[56:57], v[112:113], v[126:127] neg_lo:[0,0,1] neg_hi:[0,0,1]
	v_pk_fma_f32 v[50:51], v[50:51], v[114:115], v[128:129]
	v_pk_fma_f32 v[48:49], v[48:49], v[112:113], v[130:131]
	v_pk_fma_f32 v[46:47], v[46:47], v[110:111], v[132:133] neg_lo:[0,0,1] neg_hi:[0,0,1]
	v_pk_fma_f32 v[44:45], v[44:45], v[108:109], v[134:135] neg_lo:[0,0,1] neg_hi:[0,0,1]
	v_pk_fma_f32 v[38:39], v[38:39], v[110:111], v[84:85]
	v_pk_fma_f32 v[36:37], v[36:37], v[108:109], v[82:83]
	v_pk_fma_f32 v[42:43], v[42:43], v[114:115], v[136:137] neg_lo:[0,0,1] neg_hi:[0,0,1]
	v_pk_fma_f32 v[40:41], v[40:41], v[112:113], v[138:139] neg_lo:[0,0,1] neg_hi:[0,0,1]
	v_pk_fma_f32 v[34:35], v[34:35], v[114:115], v[106:107]
	v_pk_fma_f32 v[32:33], v[32:33], v[112:113], v[104:105]

.LBB0_1615:
	s_add_i32 s41, s39, 0x8000
	s_and_b32 s40, s41, 0x8000
	s_add_i32 s40, s40, 0
	v_add_u32_e32 v111, s40, v82
	v_lshl_add_u64 v[76:77], v[72:73], 0, s[28:29]
	v_readfirstlane_b32 s42, v111
	v_add_u32_e32 v112, 0x4000, v111
	v_lshl_add_u64 v[78:79], v[74:75], 0, s[28:29]
	v_lshl_add_u64 v[80:81], v[76:77], 0, s[10:11]
	v_add_u32_e32 v113, 0x1000, v111
	v_readfirstlane_b32 s43, v112
	s_mov_b32 m0, s42
	s_waitcnt vmcnt(0) lgkmcnt(0)
	s_barrier
	v_lshl_add_u64 v[100:101], v[78:79], 0, s[12:13]
	v_add_u32_e32 v114, 0x5000, v111
	v_readfirstlane_b32 s44, v113
	global_load_lds_dwordx4 v[80:81], off
	s_mov_b32 m0, s43
	v_lshl_add_u64 v[102:103], v[76:77], 0, s[14:15]
	v_add_u32_e32 v115, 0x2000, v111
	v_readfirstlane_b32 s45, v114
	global_load_lds_dwordx4 v[100:101], off
	s_mov_b32 m0, s44
	v_lshl_add_u64 v[104:105], v[78:79], 0, s[16:17]
	v_add_u32_e32 v116, 0x6000, v111
	v_readfirstlane_b32 s46, v115
	global_load_lds_dwordx4 v[102:103], off
	s_mov_b32 m0, s45
	v_lshl_add_u64 v[106:107], v[76:77], 0, s[18:19]
	v_add_u32_e32 v117, 0x3000, v111
	v_readfirstlane_b32 s47, v116
	global_load_lds_dwordx4 v[104:105], off
	s_mov_b32 m0, s46
	v_lshl_add_u64 v[108:109], v[78:79], 0, s[20:21]
	v_add_u32_e32 v111, 0x7000, v111
	v_readfirstlane_b32 s48, v117
	global_load_lds_dwordx4 v[106:107], off
	s_mov_b32 m0, s47
	v_lshl_add_u64 v[76:77], v[76:77], 0, s[22:23]
	v_readfirstlane_b32 s49, v111
	global_load_lds_dwordx4 v[108:109], off
	s_mov_b32 m0, s48
	v_lshl_add_u64 v[78:79], v[78:79], 0, s[24:25]
	global_load_lds_dwordx4 v[76:77], off
	s_mov_b32 m0, s49
	s_and_b32 s39, s39, 0x8000
	global_load_lds_dwordx4 v[78:79], off
	s_add_i32 s39, s39, 0
	v_add3_u32 v145, s39, v84, v85
	v_add3_u32 v178, s39, v85, v86
	v_add3_u32 v179, s39, v84, v87
	v_add3_u32 v180, s39, v86, v87
	ds_read_b128 v[104:107], v178
	ds_read_b128 v[76:79], v145 offset:16384
	ds_read_b128 v[100:103], v145 offset:18432
	ds_read_b128 v[108:111], v178 offset:2048
	ds_read_b128 v[112:115], v145 offset:20480
	ds_read_b128 v[116:119], v145 offset:22528
	ds_read_b128 v[120:123], v145 offset:24576
	ds_read_b128 v[124:127], v145 offset:26624
	ds_read_b128 v[128:131], v145 offset:28672
	ds_read_b128 v[132:135], v145 offset:30720
	ds_read_b128 v[146:149], v180
	ds_read_b128 v[136:139], v179 offset:16384
	ds_read_b128 v[140:143], v179 offset:18432
	ds_read_b128 v[150:153], v180 offset:2048
	ds_read_b128 v[154:157], v179 offset:20480
	ds_read_b128 v[158:161], v179 offset:22528
	ds_read_b128 v[162:165], v179 offset:24576
	ds_read_b128 v[166:169], v179 offset:26624
	ds_read_b128 v[170:173], v179 offset:28672
	ds_read_b128 v[174:177], v179 offset:30720
	s_add_u32 s28, s28, 0x80
	s_addc_u32 s29, s29, 0
	s_cmpk_eq_i32 s28, 0x780
	s_mov_b32 s39, s41
	s_waitcnt lgkmcnt(15)
	v_mfma_f32_16x16x32_bf16 v[60:63], v[76:79], v[104:107], v[60:63]
	v_mfma_f32_16x16x32_bf16 v[56:59], v[100:103], v[104:107], v[56:59]
	v_mfma_f32_16x16x32_bf16 v[24:27], v[76:79], v[108:111], v[24:27]
	v_mfma_f32_16x16x32_bf16 v[20:23], v[100:103], v[108:111], v[20:23]
	v_mfma_f32_16x16x32_bf16 v[52:55], v[112:115], v[104:107], v[52:55]
	v_mfma_f32_16x16x32_bf16 v[16:19], v[112:115], v[108:111], v[16:19]
	s_waitcnt lgkmcnt(14)
	v_mfma_f32_16x16x32_bf16 v[48:51], v[116:119], v[104:107], v[48:51]
	v_mfma_f32_16x16x32_bf16 v[12:15], v[116:119], v[108:111], v[12:15]
	s_waitcnt lgkmcnt(13)
	v_mfma_f32_16x16x32_bf16 v[44:47], v[120:123], v[104:107], v[44:47]
	v_mfma_f32_16x16x32_bf16 v[8:11], v[120:123], v[108:111], v[8:11]
	s_waitcnt lgkmcnt(12)
	v_mfma_f32_16x16x32_bf16 v[40:43], v[124:127], v[104:107], v[40:43]
	v_mfma_f32_16x16x32_bf16 v[4:7], v[124:127], v[108:111], v[4:7]
	s_waitcnt lgkmcnt(11)
	v_mfma_f32_16x16x32_bf16 v[32:35], v[128:131], v[104:107], v[32:35]
	v_mfma_f32_16x16x32_bf16 v[0:3], v[128:131], v[108:111], v[0:3]
	s_waitcnt lgkmcnt(10)
	v_mfma_f32_16x16x32_bf16 v[28:31], v[132:135], v[104:107], v[28:31]
	v_mfma_f32_16x16x32_bf16 v[36:39], v[132:135], v[108:111], v[36:39]
	s_waitcnt lgkmcnt(8)
	v_mfma_f32_16x16x32_bf16 v[60:63], v[136:139], v[146:149], v[60:63]
	s_waitcnt lgkmcnt(7)
	v_mfma_f32_16x16x32_bf16 v[56:59], v[140:143], v[146:149], v[56:59]
	s_waitcnt lgkmcnt(6)
	v_mfma_f32_16x16x32_bf16 v[24:27], v[136:139], v[150:153], v[24:27]
	v_mfma_f32_16x16x32_bf16 v[20:23], v[140:143], v[150:153], v[20:23]
	s_waitcnt lgkmcnt(5)
	v_mfma_f32_16x16x32_bf16 v[52:55], v[154:157], v[146:149], v[52:55]
	v_mfma_f32_16x16x32_bf16 v[16:19], v[154:157], v[150:153], v[16:19]
	s_waitcnt lgkmcnt(4)
	v_mfma_f32_16x16x32_bf16 v[48:51], v[158:161], v[146:149], v[48:51]
	v_mfma_f32_16x16x32_bf16 v[12:15], v[158:161], v[150:153], v[12:15]
	s_waitcnt lgkmcnt(3)
	v_mfma_f32_16x16x32_bf16 v[44:47], v[162:165], v[146:149], v[44:47]
	v_mfma_f32_16x16x32_bf16 v[8:11], v[162:165], v[150:153], v[8:11]
	s_waitcnt lgkmcnt(2)
	v_mfma_f32_16x16x32_bf16 v[40:43], v[166:169], v[146:149], v[40:43]
	v_mfma_f32_16x16x32_bf16 v[4:7], v[166:169], v[150:153], v[4:7]
	s_waitcnt lgkmcnt(1)
	v_mfma_f32_16x16x32_bf16 v[32:35], v[170:173], v[146:149], v[32:35]
	v_mfma_f32_16x16x32_bf16 v[0:3], v[170:173], v[150:153], v[0:3]
	s_waitcnt lgkmcnt(0)
	v_mfma_f32_16x16x32_bf16 v[28:31], v[174:177], v[146:149], v[28:31]
	v_mfma_f32_16x16x32_bf16 v[36:39], v[174:177], v[150:153], v[36:39]
	s_cbranch_scc0 .LBB0_1615
	v_add_u32_e32 v80, s40, v84
	v_add_u32_e32 v81, v80, v85
	s_waitcnt vmcnt(0)
	s_barrier
	ds_read_b128 v[72:75], v81 offset:16384
	v_add3_u32 v99, s40, v85, v86
	ds_read_b128 v[76:79], v81 offset:18432
	ds_read_b128 v[100:103], v99
	ds_read_b128 v[104:107], v99 offset:2048
	ds_read_b128 v[108:111], v81 offset:20480
	ds_read_b128 v[112:115], v81 offset:22528
	ds_read_b128 v[116:119], v81 offset:24576
	ds_read_b128 v[120:123], v81 offset:26624
	ds_read_b128 v[124:127], v81 offset:28672
	ds_read_b128 v[128:131], v81 offset:30720
	v_add_u32_e32 v80, v80, v87
	s_waitcnt lgkmcnt(7)
	v_mfma_f32_16x16x32_bf16 v[60:63], v[72:75], v[100:103], v[60:63]
	s_lshl_b32 s38, s38, 7
	v_mfma_f32_16x16x32_bf16 v[56:59], v[76:79], v[100:103], v[56:59]
	s_waitcnt lgkmcnt(4)
	v_mfma_f32_16x16x32_bf16 v[48:51], v[112:115], v[100:103], v[48:51]
	s_waitcnt lgkmcnt(3)
	v_mfma_f32_16x16x32_bf16 v[44:47], v[116:119], v[100:103], v[44:47]
	s_waitcnt lgkmcnt(2)
	v_mfma_f32_16x16x32_bf16 v[40:43], v[120:123], v[100:103], v[40:43]
	s_waitcnt lgkmcnt(1)
	v_mfma_f32_16x16x32_bf16 v[32:35], v[124:127], v[100:103], v[32:35]
	s_waitcnt lgkmcnt(0)
	v_mfma_f32_16x16x32_bf16 v[28:31], v[128:131], v[100:103], v[28:31]
	v_mfma_f32_16x16x32_bf16 v[24:27], v[72:75], v[104:107], v[24:27]
	ds_read_b128 v[72:75], v80 offset:16384
	v_mfma_f32_16x16x32_bf16 v[52:55], v[108:111], v[100:103], v[52:55]
	v_mfma_f32_16x16x32_bf16 v[20:23], v[76:79], v[104:107], v[20:23]
	v_mfma_f32_16x16x32_bf16 v[16:19], v[108:111], v[104:107], v[16:19]
	v_mfma_f32_16x16x32_bf16 v[12:15], v[112:115], v[104:107], v[12:15]
	v_mfma_f32_16x16x32_bf16 v[8:11], v[116:119], v[104:107], v[8:11]
	v_mfma_f32_16x16x32_bf16 v[4:7], v[120:123], v[104:107], v[4:7]
	v_mfma_f32_16x16x32_bf16 v[0:3], v[124:127], v[104:107], v[0:3]
	v_mfma_f32_16x16x32_bf16 v[100:103], v[128:131], v[104:107], v[36:39]
	s_nop 2
	v_add3_u32 v36, s40, v87, v86
	ds_read_b128 v[76:79], v80 offset:18432
	ds_read_b128 v[104:107], v36
	ds_read_b128 v[108:111], v36 offset:2048
	ds_read_b128 v[128:131], v80 offset:28672
	ds_read_b128 v[132:135], v80 offset:30720
	ds_read_b128 v[112:115], v80 offset:20480
	ds_read_b128 v[116:119], v80 offset:22528
	ds_read_b128 v[120:123], v80 offset:24576
	ds_read_b128 v[124:127], v80 offset:26624
	s_waitcnt lgkmcnt(7)
	v_mfma_f32_16x16x32_bf16 v[60:63], v[72:75], v[104:107], v[60:63]
	s_waitcnt lgkmcnt(5)
	v_mfma_f32_16x16x32_bf16 v[36:39], v[128:131], v[104:107], v[32:35]
	s_waitcnt lgkmcnt(4)
	v_mfma_f32_16x16x32_bf16 v[32:35], v[132:135], v[104:107], v[28:31]
	v_mfma_f32_16x16x32_bf16 v[28:31], v[72:75], v[108:111], v[24:27]
	v_add_u32_e32 v72, s38, v83
	v_mul_hi_i32 v73, v72, s31
	v_mfma_f32_16x16x32_bf16 v[24:27], v[76:79], v[108:111], v[20:23]
	s_waitcnt lgkmcnt(3)
	v_mfma_f32_16x16x32_bf16 v[20:23], v[112:115], v[108:111], v[16:19]
	s_waitcnt lgkmcnt(2)
	v_mfma_f32_16x16x32_bf16 v[16:19], v[116:119], v[108:111], v[12:15]
	s_waitcnt lgkmcnt(1)
	v_mfma_f32_16x16x32_bf16 v[12:15], v[120:123], v[108:111], v[8:11]
	s_waitcnt lgkmcnt(0)
	v_mfma_f32_16x16x32_bf16 v[8:11], v[124:127], v[108:111], v[4:7]
	s_nop 2
	v_lshrrev_b32_e32 v4, 31, v73
	v_ashrrev_i32_e32 v5, 11, v73
	v_mfma_f32_16x16x32_bf16 v[56:59], v[76:79], v[104:107], v[56:59]
	v_add_u32_e32 v73, v5, v4
	v_mad_i32_i24 v78, v73, s33, v72
	v_lshlrev_b32_e32 v75, 13, v73
	v_mfma_f32_16x16x32_bf16 v[52:55], v[112:115], v[104:107], v[52:55]
	v_cmp_lt_i32_e32 vcc, s34, v78
	v_add3_u32 v74, v75, v78, s35
	v_mfma_f32_16x16x32_bf16 v[48:51], v[116:119], v[104:107], v[48:51]
	v_mfma_f32_16x16x32_bf16 v[44:47], v[120:123], v[104:107], v[44:47]
	v_mfma_f32_16x16x32_bf16 v[40:43], v[124:127], v[104:107], v[40:43]
	v_mfma_f32_16x16x32_bf16 v[4:7], v[128:131], v[108:111], v[0:3]
	v_mfma_f32_16x16x32_bf16 v[0:3], v[132:135], v[108:111], v[100:103]
	s_and_saveexec_b64 s[28:29], vcc
	s_xor_b64 s[28:29], exec, s[28:29]
	v_add3_u32 v72, v75, v78, s35
	s_or_saveexec_b64 s[28:29], s[28:29]
	v_mov_b64_e32 v[76:77], s[92:93]
	v_lshl_add_u32 v75, v73, 8, v78
	s_xor_b64 exec, exec, s[28:29]
	v_lshl_add_u32 v72, v73, 8, v78
	v_mov_b64_e32 v[76:77], s[2:3]
	s_or_b64 exec, exec, s[28:29]
	s_and_saveexec_b64 s[28:29], vcc
	s_xor_b64 s[28:29], exec, s[28:29]
	s_cbranch_execz .LBB0_1622
	v_add_u32_e32 v73, 3, v73
	v_mul_hi_i32_i24_e32 v79, 0x6000, v73
	v_mul_i32_i24_e32 v78, 0x6000, v73
	s_or_saveexec_b64 s[28:29], s[28:29]
	v_mov_b64_e32 v[80:81], s[92:93]
	s_xor_b64 exec, exec, s[28:29]
	s_cbranch_execnz .LBB0_1623
	s_branch .LBB0_1624

.LBB0_1759:
	s_add_i32 s36, s34, 0x8000
	s_and_b32 s35, s36, 0x8000
	s_add_i32 s35, s35, 0
	v_add_u32_e32 v111, s35, v78
	v_lshl_add_u64 v[94:95], v[74:75], 0, s[26:27]
	v_readfirstlane_b32 s37, v111
	v_add_u32_e32 v112, 0x4000, v111
	v_lshl_add_u64 v[96:97], v[76:77], 0, s[26:27]
	v_lshl_add_u64 v[98:99], v[94:95], 0, s[10:11]
	v_add_u32_e32 v113, 0x1000, v111
	v_readfirstlane_b32 s38, v112
	s_mov_b32 m0, s37
	s_waitcnt vmcnt(0) lgkmcnt(0)
	s_barrier
	v_lshl_add_u64 v[100:101], v[96:97], 0, s[12:13]
	v_add_u32_e32 v114, 0x5000, v111
	v_readfirstlane_b32 s39, v113
	global_load_lds_dwordx4 v[98:99], off
	s_mov_b32 m0, s38
	v_lshl_add_u64 v[102:103], v[94:95], 0, s[14:15]
	v_add_u32_e32 v115, 0x2000, v111
	v_readfirstlane_b32 s40, v114
	global_load_lds_dwordx4 v[100:101], off
	s_mov_b32 m0, s39
	v_lshl_add_u64 v[104:105], v[96:97], 0, s[16:17]
	v_add_u32_e32 v116, 0x6000, v111
	v_readfirstlane_b32 s41, v115
	global_load_lds_dwordx4 v[102:103], off
	s_mov_b32 m0, s40
	v_lshl_add_u64 v[106:107], v[94:95], 0, s[18:19]
	v_add_u32_e32 v117, 0x3000, v111
	v_readfirstlane_b32 s42, v116
	global_load_lds_dwordx4 v[104:105], off
	s_mov_b32 m0, s41
	v_lshl_add_u64 v[108:109], v[96:97], 0, s[20:21]
	v_add_u32_e32 v111, 0x7000, v111
	v_readfirstlane_b32 s43, v117
	global_load_lds_dwordx4 v[106:107], off
	s_mov_b32 m0, s42
	v_lshl_add_u64 v[94:95], v[94:95], 0, s[22:23]
	v_readfirstlane_b32 s44, v111
	global_load_lds_dwordx4 v[108:109], off
	s_mov_b32 m0, s43
	v_lshl_add_u64 v[96:97], v[96:97], 0, s[24:25]
	global_load_lds_dwordx4 v[94:95], off
	s_mov_b32 m0, s44
	s_and_b32 s34, s34, 0x8000
	global_load_lds_dwordx4 v[96:97], off
	s_add_i32 s34, s34, 0
	v_add3_u32 v143, s34, v80, v81
	v_add3_u32 v145, s34, v81, v82
	v_add3_u32 v206, s34, v80, v83
	v_add3_u32 v207, s34, v82, v83
	ds_read_b128 v[102:105], v145
	ds_read_b128 v[94:97], v143 offset:16384
	ds_read_b128 v[98:101], v143 offset:18432
	ds_read_b128 v[106:109], v145 offset:2048
	ds_read_b128 v[110:113], v143 offset:20480
	ds_read_b128 v[114:117], v143 offset:22528
	ds_read_b128 v[118:121], v143 offset:24576
	ds_read_b128 v[122:125], v143 offset:26624
	ds_read_b128 v[126:129], v143 offset:28672
	ds_read_b128 v[130:133], v143 offset:30720
	ds_read_b128 v[174:177], v207
	ds_read_b128 v[166:169], v206 offset:16384
	ds_read_b128 v[170:173], v206 offset:18432
	ds_read_b128 v[178:181], v207 offset:2048
	ds_read_b128 v[182:185], v206 offset:20480
	ds_read_b128 v[186:189], v206 offset:22528
	ds_read_b128 v[190:193], v206 offset:24576
	ds_read_b128 v[194:197], v206 offset:26624
	ds_read_b128 v[198:201], v206 offset:28672
	ds_read_b128 v[202:205], v206 offset:30720
	s_add_u32 s26, s26, 0x80
	s_addc_u32 s27, s27, 0
	s_cmpk_eq_i32 s26, 0x780
	s_mov_b32 s34, s36
	s_waitcnt lgkmcnt(15)
	v_mfma_f32_16x16x32_bf16 v[60:63], v[94:97], v[102:105], v[60:63]
	v_mfma_f32_16x16x32_bf16 v[56:59], v[98:101], v[102:105], v[56:59]
	v_mfma_f32_16x16x32_bf16 v[28:31], v[94:97], v[106:109], v[28:31]
	v_mfma_f32_16x16x32_bf16 v[24:27], v[98:101], v[106:109], v[24:27]
	v_mfma_f32_16x16x32_bf16 v[52:55], v[110:113], v[102:105], v[52:55]
	v_mfma_f32_16x16x32_bf16 v[20:23], v[110:113], v[106:109], v[20:23]
	s_waitcnt lgkmcnt(14)
	v_mfma_f32_16x16x32_bf16 v[48:51], v[114:117], v[102:105], v[48:51]
	v_mfma_f32_16x16x32_bf16 v[12:15], v[114:117], v[106:109], v[12:15]
	s_waitcnt lgkmcnt(13)
	v_mfma_f32_16x16x32_bf16 v[44:47], v[118:121], v[102:105], v[44:47]
	v_mfma_f32_16x16x32_bf16 v[8:11], v[118:121], v[106:109], v[8:11]
	s_waitcnt lgkmcnt(12)
	v_mfma_f32_16x16x32_bf16 v[40:43], v[122:125], v[102:105], v[40:43]
	v_mfma_f32_16x16x32_bf16 v[4:7], v[122:125], v[106:109], v[4:7]
	s_waitcnt lgkmcnt(11)
	v_mfma_f32_16x16x32_bf16 v[36:39], v[126:129], v[102:105], v[36:39]
	v_mfma_f32_16x16x32_bf16 v[0:3], v[126:129], v[106:109], v[0:3]
	s_waitcnt lgkmcnt(10)
	v_mfma_f32_16x16x32_bf16 v[32:35], v[130:133], v[102:105], v[32:35]
	v_mfma_f32_16x16x32_bf16 v[16:19], v[130:133], v[106:109], v[16:19]
	s_waitcnt lgkmcnt(8)
	v_mfma_f32_16x16x32_bf16 v[60:63], v[166:169], v[174:177], v[60:63]
	s_waitcnt lgkmcnt(7)
	v_mfma_f32_16x16x32_bf16 v[56:59], v[170:173], v[174:177], v[56:59]
	s_waitcnt lgkmcnt(6)
	v_mfma_f32_16x16x32_bf16 v[28:31], v[166:169], v[178:181], v[28:31]
	v_mfma_f32_16x16x32_bf16 v[24:27], v[170:173], v[178:181], v[24:27]
	s_waitcnt lgkmcnt(5)
	v_mfma_f32_16x16x32_bf16 v[52:55], v[182:185], v[174:177], v[52:55]
	v_mfma_f32_16x16x32_bf16 v[20:23], v[182:185], v[178:181], v[20:23]
	s_waitcnt lgkmcnt(4)
	v_mfma_f32_16x16x32_bf16 v[48:51], v[186:189], v[174:177], v[48:51]
	v_mfma_f32_16x16x32_bf16 v[12:15], v[186:189], v[178:181], v[12:15]
	s_waitcnt lgkmcnt(3)
	v_mfma_f32_16x16x32_bf16 v[44:47], v[190:193], v[174:177], v[44:47]
	v_mfma_f32_16x16x32_bf16 v[8:11], v[190:193], v[178:181], v[8:11]
	s_waitcnt lgkmcnt(2)
	v_mfma_f32_16x16x32_bf16 v[40:43], v[194:197], v[174:177], v[40:43]
	v_mfma_f32_16x16x32_bf16 v[4:7], v[194:197], v[178:181], v[4:7]
	s_waitcnt lgkmcnt(1)
	v_mfma_f32_16x16x32_bf16 v[36:39], v[198:201], v[174:177], v[36:39]
	v_mfma_f32_16x16x32_bf16 v[0:3], v[198:201], v[178:181], v[0:3]
	s_waitcnt lgkmcnt(0)
	v_mfma_f32_16x16x32_bf16 v[32:35], v[202:205], v[174:177], v[32:35]
	v_mfma_f32_16x16x32_bf16 v[16:19], v[202:205], v[178:181], v[16:19]
	s_cbranch_scc0 .LBB0_1759
	v_add_u32_e32 v138, s35, v80
	v_add_u32_e32 v126, v138, v81
	s_waitcnt vmcnt(0)
	s_barrier
	ds_read_b128 v[74:77], v126 offset:16384
	v_add3_u32 v102, s35, v81, v82
	ds_read_b128 v[94:97], v102
	ds_read_b128 v[98:101], v126 offset:18432
	ds_read_b128 v[102:105], v102 offset:2048
	ds_read_b128 v[106:109], v126 offset:20480
	ds_read_b128 v[110:113], v126 offset:22528
	ds_read_b128 v[114:117], v126 offset:24576
	ds_read_b128 v[118:121], v126 offset:26624
	v_add3_u32 v134, s35, v83, v82
	v_add_u32_e32 v142, v138, v83
	ds_read_b128 v[122:125], v126 offset:28672
	ds_read_b128 v[126:129], v126 offset:30720
	ds_read_b128 v[130:133], v134
	ds_read_b128 v[134:137], v134 offset:2048
	ds_read_b128 v[138:141], v142 offset:16384
	ds_read_b128 v[146:149], v142 offset:18432
	s_waitcnt lgkmcnt(11)
	v_mfma_f32_16x16x32_bf16 v[56:59], v[98:101], v[94:97], v[56:59]
	s_lshl_b32 s33, s33, 7
	s_lshl_b32 s26, s31, 7
	s_ashr_i32 s27, s26, 31
	v_mfma_f32_16x16x32_bf16 v[60:63], v[74:77], v[94:97], v[60:63]
	s_lshl_b64 s[26:27], s[26:27], 1
	s_add_i32 s30, s30, s28
	s_cmpk_gt_i32 s30, 0xfff
	s_waitcnt lgkmcnt(0)
	v_mfma_f32_16x16x32_bf16 v[56:59], v[146:149], v[130:133], v[56:59]
	v_mfma_f32_16x16x32_bf16 v[48:51], v[110:113], v[94:97], v[48:51]
	v_mfma_f32_16x16x32_bf16 v[52:55], v[106:109], v[94:97], v[52:55]
	s_nop 5
	v_max_f32_e32 v56, v56, v56
	v_max_f32_e32 v57, v57, v57
	v_max_f32_e32 v56, 0, v56
	v_mfma_f32_16x16x32_bf16 v[44:47], v[114:117], v[94:97], v[44:47]
	v_max_f32_e32 v57, 0, v57
	v_max_f32_e32 v59, v59, v59
	v_max_f32_e32 v59, 0, v59
	v_mfma_f32_16x16x32_bf16 v[40:43], v[118:121], v[94:97], v[40:43]
	v_mfma_f32_16x16x32_bf16 v[36:39], v[122:125], v[94:97], v[36:39]
	v_mfma_f32_16x16x32_bf16 v[32:35], v[126:129], v[94:97], v[32:35]
	ds_read_b128 v[94:97], v142 offset:20480
	ds_read_b128 v[150:153], v142 offset:22528
	ds_read_b128 v[154:157], v142 offset:24576
	ds_read_b128 v[158:161], v142 offset:26624
	v_mfma_f32_16x16x32_bf16 v[60:63], v[138:141], v[130:133], v[60:63]
	s_waitcnt lgkmcnt(2)
	v_mfma_f32_16x16x32_bf16 v[48:51], v[150:153], v[130:133], v[48:51]
	v_mfma_f32_16x16x32_bf16 v[20:23], v[106:109], v[102:105], v[20:23]
	v_mul_f32_e64 v106, v56, v56
	v_mul_f32_e64 v107, v57, v57
	v_max_f32_e32 v57, v58, v58
	s_nop 1
	v_max_f32_e32 v60, v60, v60
	v_mfma_f32_16x16x32_bf16 v[24:27], v[98:101], v[102:105], v[24:27]
	v_add_u32_e32 v100, s33, v79
	v_mov_b64_e32 v[98:99], s[0:1]
	v_max_f32_e32 v61, v61, v61
	v_max_f32_e32 v56, v62, v62
	v_max_f32_e32 v58, 0, v57
	v_max_f32_e32 v57, v63, v63
	v_mad_i64_i32 v[100:101], s[34:35], v100, s29, v[98:99]
	v_max_f32_e32 v60, 0, v60
	v_max_f32_e32 v61, 0, v61
	v_max_f32_e32 v56, 0, v56
	v_max_f32_e32 v57, 0, v57
	v_mfma_f32_16x16x32_bf16 v[52:55], v[94:97], v[130:133], v[52:55]
	v_lshl_add_u64 v[100:101], v[100:101], 0, s[26:27]
	v_pk_mul_f32 v[60:61], v[60:61], v[60:61]
	v_pk_mul_f32 v[62:63], v[56:57], v[56:57]
	v_mfma_f32_16x16x32_bf16 v[28:31], v[74:77], v[102:105], v[28:31]
	v_max_f32_e32 v48, v48, v48
	v_max_f32_e32 v49, v49, v49
	ds_read_b128 v[74:77], v142 offset:28672
	ds_read_b128 v[162:165], v142 offset:30720
	v_mfma_f32_16x16x32_bf16 v[12:15], v[110:113], v[102:105], v[12:15]
	v_lshl_add_u64 v[100:101], v[100:101], 0, v[64:65]
	v_cvt_pk_bf16_f32 v56, v60, v61
	v_cvt_pk_bf16_f32 v57, v62, v63
	v_mfma_f32_16x16x32_bf16 v[8:11], v[114:117], v[102:105], v[8:11]
	v_max_f32_e32 v48, 0, v48
	v_max_f32_e32 v49, 0, v49
	v_max_f32_e32 v52, v52, v52
	v_mfma_f32_16x16x32_bf16 v[4:7], v[118:121], v[102:105], v[4:7]
	v_max_f32_e32 v53, v53, v53
	v_max_f32_e32 v51, v51, v51
	v_max_f32_e32 v52, 0, v52
	v_mfma_f32_16x16x32_bf16 v[0:3], v[122:125], v[102:105], v[0:3]
	v_max_f32_e32 v53, 0, v53
	v_max_f32_e32 v51, 0, v51
	v_pk_mul_f32 v[52:53], v[52:53], v[52:53]
	v_mfma_f32_16x16x32_bf16 v[16:19], v[126:129], v[102:105], v[16:19]
	v_mul_f32_e64 v102, v58, v58
	v_mul_f32_e64 v103, v59, v59
	v_cvt_pk_bf16_f32 v58, v106, v107
	v_cvt_pk_bf16_f32 v59, v102, v103
	s_waitcnt lgkmcnt(2)
	v_mfma_f32_16x16x32_bf16 v[40:43], v[158:161], v[130:133], v[40:43]
	global_store_dwordx4 v[100:101], v[56:59], off
	s_nop 1
	v_pk_mul_f32 v[56:57], v[48:49], v[48:49]
	v_max_f32_e32 v49, v50, v50
	v_max_f32_e32 v48, v54, v54
	v_max_f32_e32 v50, 0, v49
	v_max_f32_e32 v49, v55, v55
	v_mfma_f32_16x16x32_bf16 v[44:47], v[154:157], v[130:133], v[44:47]
	v_max_f32_e32 v48, 0, v48
	v_max_f32_e32 v49, 0, v49
	v_pk_mul_f32 v[54:55], v[48:49], v[48:49]
	v_pk_mul_f32 v[58:59], v[50:51], v[50:51]
	v_max_f32_e32 v40, v40, v40
	v_max_f32_e32 v41, v41, v41
	s_waitcnt lgkmcnt(0)
	v_mfma_f32_16x16x32_bf16 v[32:35], v[162:165], v[130:133], v[32:35]
	v_cvt_pk_bf16_f32 v48, v52, v53
	v_cvt_pk_bf16_f32 v49, v54, v55
	v_cvt_pk_bf16_f32 v50, v56, v57
	v_cvt_pk_bf16_f32 v51, v58, v59
	v_max_f32_e32 v40, 0, v40
	v_max_f32_e32 v41, 0, v41
	global_store_dwordx4 v[100:101], v[48:51], off offset:64
	v_max_f32_e32 v44, v44, v44
	v_max_f32_e32 v45, v45, v45
	v_pk_mul_f32 v[48:49], v[40:41], v[40:41]
	v_max_f32_e32 v41, v42, v42
	v_max_f32_e32 v40, v46, v46
	v_max_f32_e32 v42, 0, v41
	v_max_f32_e32 v41, v47, v47
	v_max_f32_e32 v43, v43, v43
	v_mfma_f32_16x16x32_bf16 v[36:39], v[74:77], v[130:133], v[36:39]
	v_max_f32_e32 v44, 0, v44
	v_max_f32_e32 v45, 0, v45
	v_max_f32_e32 v40, 0, v40
	v_max_f32_e32 v41, 0, v41
	v_max_f32_e32 v43, 0, v43
	v_pk_mul_f32 v[44:45], v[44:45], v[44:45]
	v_pk_mul_f32 v[46:47], v[40:41], v[40:41]
	v_pk_mul_f32 v[50:51], v[42:43], v[42:43]
	v_max_f32_e32 v32, v32, v32
	v_max_f32_e32 v33, v33, v33
	v_mfma_f32_16x16x32_bf16 v[24:27], v[146:149], v[134:137], v[24:27]
	v_cvt_pk_bf16_f32 v40, v44, v45
	v_cvt_pk_bf16_f32 v41, v46, v47
	v_cvt_pk_bf16_f32 v42, v48, v49
	v_cvt_pk_bf16_f32 v43, v50, v51
	v_max_f32_e32 v32, 0, v32
	v_max_f32_e32 v33, 0, v33
	global_store_dwordx4 v[100:101], v[40:43], off offset:128
	v_max_f32_e32 v36, v36, v36
	v_max_f32_e32 v37, v37, v37
	v_pk_mul_f32 v[40:41], v[32:33], v[32:33]
	v_max_f32_e32 v33, v34, v34
	v_max_f32_e32 v32, v38, v38
	v_max_f32_e32 v34, 0, v33
	v_max_f32_e32 v33, v39, v39
	v_max_f32_e32 v35, v35, v35
	v_mfma_f32_16x16x32_bf16 v[28:31], v[138:141], v[134:137], v[28:31]
	v_max_f32_e32 v36, 0, v36
	v_max_f32_e32 v37, 0, v37
	v_max_f32_e32 v32, 0, v32
	v_max_f32_e32 v33, 0, v33
	v_max_f32_e32 v35, 0, v35
	v_pk_mul_f32 v[36:37], v[36:37], v[36:37]
	v_pk_mul_f32 v[38:39], v[32:33], v[32:33]
	v_pk_mul_f32 v[42:43], v[34:35], v[34:35]
	v_max_f32_e32 v24, v24, v24
	v_max_f32_e32 v25, v25, v25
	v_mfma_f32_16x16x32_bf16 v[12:15], v[150:153], v[134:137], v[12:15]
	v_cvt_pk_bf16_f32 v32, v36, v37
	v_cvt_pk_bf16_f32 v33, v38, v39
	v_cvt_pk_bf16_f32 v34, v40, v41
	v_cvt_pk_bf16_f32 v35, v42, v43
	v_max_f32_e32 v24, 0, v24
	v_max_f32_e32 v25, 0, v25
	global_store_dwordx4 v[100:101], v[32:35], off offset:192
	v_max_f32_e32 v28, v28, v28
	v_max_f32_e32 v29, v29, v29
	v_pk_mul_f32 v[34:35], v[24:25], v[24:25]
	v_max_f32_e32 v25, v26, v26
	v_add_u32_e32 v32, s33, v84
	v_max_f32_e32 v24, v30, v30
	v_max_f32_e32 v26, 0, v25
	v_max_f32_e32 v25, v31, v31
	v_max_f32_e32 v27, v27, v27
	v_mfma_f32_16x16x32_bf16 v[20:23], v[94:97], v[134:137], v[20:23]
	v_mad_i64_i32 v[32:33], s[34:35], v32, s29, v[98:99]
	v_max_f32_e32 v28, 0, v28
	v_max_f32_e32 v29, 0, v29
	v_max_f32_e32 v24, 0, v24
	v_max_f32_e32 v25, 0, v25
	v_max_f32_e32 v27, 0, v27
	v_lshl_add_u64 v[32:33], v[32:33], 0, s[26:27]
	v_pk_mul_f32 v[28:29], v[28:29], v[28:29]
	v_pk_mul_f32 v[30:31], v[24:25], v[24:25]
	v_pk_mul_f32 v[36:37], v[26:27], v[26:27]
	v_max_f32_e32 v12, v12, v12
	v_max_f32_e32 v13, v13, v13
	v_mfma_f32_16x16x32_bf16 v[4:7], v[158:161], v[134:137], v[4:7]
	v_lshl_add_u64 v[32:33], v[32:33], 0, v[64:65]
	v_cvt_pk_bf16_f32 v24, v28, v29
	v_cvt_pk_bf16_f32 v25, v30, v31
	v_cvt_pk_bf16_f32 v26, v34, v35
	v_cvt_pk_bf16_f32 v27, v36, v37
	v_max_f32_e32 v12, 0, v12
	v_max_f32_e32 v13, 0, v13
	global_store_dwordx4 v[32:33], v[24:27], off
	v_max_f32_e32 v20, v20, v20
	v_max_f32_e32 v21, v21, v21
	v_pk_mul_f32 v[24:25], v[12:13], v[12:13]
	v_max_f32_e32 v13, v14, v14
	v_max_f32_e32 v12, v22, v22
	v_max_f32_e32 v14, 0, v13
	v_max_f32_e32 v13, v23, v23
	v_max_f32_e32 v15, v15, v15
	v_mfma_f32_16x16x32_bf16 v[8:11], v[154:157], v[134:137], v[8:11]
	v_max_f32_e32 v20, 0, v20
	v_max_f32_e32 v21, 0, v21
	v_max_f32_e32 v12, 0, v12
	v_max_f32_e32 v13, 0, v13
	v_max_f32_e32 v15, 0, v15
	v_pk_mul_f32 v[20:21], v[20:21], v[20:21]
	v_pk_mul_f32 v[22:23], v[12:13], v[12:13]
	v_pk_mul_f32 v[26:27], v[14:15], v[14:15]
	v_max_f32_e32 v4, v4, v4
	v_max_f32_e32 v5, v5, v5
	v_cvt_pk_bf16_f32 v12, v20, v21
	v_cvt_pk_bf16_f32 v13, v22, v23
	v_cvt_pk_bf16_f32 v14, v24, v25
	v_cvt_pk_bf16_f32 v15, v26, v27
	v_max_f32_e32 v4, 0, v4
	v_max_f32_e32 v5, 0, v5
	global_store_dwordx4 v[32:33], v[12:15], off offset:64
	v_mfma_f32_16x16x32_bf16 v[0:3], v[74:77], v[134:137], v[0:3]
	v_max_f32_e32 v8, v8, v8
	v_pk_mul_f32 v[12:13], v[4:5], v[4:5]
	v_max_f32_e32 v5, v6, v6
	v_mfma_f32_16x16x32_bf16 v[16:19], v[162:165], v[134:137], v[16:19]
	v_max_f32_e32 v9, v9, v9
	v_max_f32_e32 v4, v10, v10
	v_max_f32_e32 v6, 0, v5
	v_max_f32_e32 v5, v11, v11
	v_max_f32_e32 v7, v7, v7
	v_max_f32_e32 v8, 0, v8
	v_max_f32_e32 v9, 0, v9
	v_max_f32_e32 v4, 0, v4
	v_max_f32_e32 v5, 0, v5
	v_max_f32_e32 v7, 0, v7
	v_pk_mul_f32 v[8:9], v[8:9], v[8:9]
	v_pk_mul_f32 v[10:11], v[4:5], v[4:5]
	v_pk_mul_f32 v[14:15], v[6:7], v[6:7]
	v_cvt_pk_bf16_f32 v4, v8, v9
	v_cvt_pk_bf16_f32 v5, v10, v11
	v_cvt_pk_bf16_f32 v6, v12, v13
	v_cvt_pk_bf16_f32 v7, v14, v15
	global_store_dwordx4 v[32:33], v[4:7], off offset:128
	v_max_f32_e32 v0, v0, v0
	v_max_f32_e32 v1, v1, v1
	v_max_f32_e32 v4, v16, v16
	v_max_f32_e32 v5, v17, v17
	v_max_f32_e32 v2, v2, v2
	v_max_f32_e32 v6, v18, v18
	v_max_f32_e32 v3, v3, v3
	v_max_f32_e32 v7, v19, v19
	v_max_f32_e32 v0, 0, v0
	v_max_f32_e32 v4, 0, v4
	v_max_f32_e32 v1, 0, v1
	v_max_f32_e32 v5, 0, v5
	v_max_f32_e32 v2, 0, v2
	v_max_f32_e32 v6, 0, v6
	v_max_f32_e32 v3, 0, v3
	v_max_f32_e32 v7, 0, v7
	v_pk_mul_f32 v[0:1], v[0:1], v[0:1]
	v_pk_mul_f32 v[4:5], v[4:5], v[4:5]
	v_pk_mul_f32 v[2:3], v[2:3], v[2:3]
	v_pk_mul_f32 v[6:7], v[6:7], v[6:7]
	v_cvt_pk_bf16_f32 v0, v0, v1
	v_cvt_pk_bf16_f32 v1, v2, v3
	v_cvt_pk_bf16_f32 v2, v4, v5
	v_cvt_pk_bf16_f32 v3, v6, v7
	global_store_dwordx4 v[32:33], v[0:3], off offset:192
	s_cbranch_scc0 .LBB0_1754

.LBB0_1824:
	s_add_i32 s41, s39, 0x8000
	s_and_b32 s40, s41, 0x8000
	s_add_i32 s40, s40, 0
	v_add_u32_e32 v111, s40, v82
	v_lshl_add_u64 v[76:77], v[72:73], 0, s[28:29]
	v_readfirstlane_b32 s42, v111
	v_add_u32_e32 v112, 0x4000, v111
	v_lshl_add_u64 v[78:79], v[74:75], 0, s[28:29]
	v_lshl_add_u64 v[80:81], v[76:77], 0, s[10:11]
	v_add_u32_e32 v113, 0x1000, v111
	v_readfirstlane_b32 s43, v112
	s_mov_b32 m0, s42
	s_waitcnt vmcnt(0) lgkmcnt(0)
	s_barrier
	v_lshl_add_u64 v[100:101], v[78:79], 0, s[12:13]
	v_add_u32_e32 v114, 0x5000, v111
	v_readfirstlane_b32 s44, v113
	global_load_lds_dwordx4 v[80:81], off
	s_mov_b32 m0, s43
	v_lshl_add_u64 v[102:103], v[76:77], 0, s[14:15]
	v_add_u32_e32 v115, 0x2000, v111
	v_readfirstlane_b32 s45, v114
	global_load_lds_dwordx4 v[100:101], off
	s_mov_b32 m0, s44
	v_lshl_add_u64 v[104:105], v[78:79], 0, s[16:17]
	v_add_u32_e32 v116, 0x6000, v111
	v_readfirstlane_b32 s46, v115
	global_load_lds_dwordx4 v[102:103], off
	s_mov_b32 m0, s45
	v_lshl_add_u64 v[106:107], v[76:77], 0, s[18:19]
	v_add_u32_e32 v117, 0x3000, v111
	v_readfirstlane_b32 s47, v116
	global_load_lds_dwordx4 v[104:105], off
	s_mov_b32 m0, s46
	v_lshl_add_u64 v[108:109], v[78:79], 0, s[20:21]
	v_add_u32_e32 v111, 0x7000, v111
	v_readfirstlane_b32 s48, v117
	global_load_lds_dwordx4 v[106:107], off
	s_mov_b32 m0, s47
	v_lshl_add_u64 v[76:77], v[76:77], 0, s[22:23]
	v_readfirstlane_b32 s49, v111
	global_load_lds_dwordx4 v[108:109], off
	s_mov_b32 m0, s48
	v_lshl_add_u64 v[78:79], v[78:79], 0, s[24:25]
	global_load_lds_dwordx4 v[76:77], off
	s_mov_b32 m0, s49
	s_and_b32 s39, s39, 0x8000
	global_load_lds_dwordx4 v[78:79], off
	s_add_i32 s39, s39, 0
	v_add3_u32 v145, s39, v84, v85
	v_add3_u32 v178, s39, v85, v86
	v_add3_u32 v179, s39, v84, v87
	v_add3_u32 v180, s39, v86, v87
	ds_read_b128 v[104:107], v178
	ds_read_b128 v[76:79], v145 offset:16384
	ds_read_b128 v[100:103], v145 offset:18432
	ds_read_b128 v[108:111], v178 offset:2048
	ds_read_b128 v[112:115], v145 offset:20480
	ds_read_b128 v[116:119], v145 offset:22528
	ds_read_b128 v[120:123], v145 offset:24576
	ds_read_b128 v[124:127], v145 offset:26624
	ds_read_b128 v[128:131], v145 offset:28672
	ds_read_b128 v[132:135], v145 offset:30720
	ds_read_b128 v[146:149], v180
	ds_read_b128 v[136:139], v179 offset:16384
	ds_read_b128 v[140:143], v179 offset:18432
	ds_read_b128 v[150:153], v180 offset:2048
	ds_read_b128 v[154:157], v179 offset:20480
	ds_read_b128 v[158:161], v179 offset:22528
	ds_read_b128 v[162:165], v179 offset:24576
	ds_read_b128 v[166:169], v179 offset:26624
	ds_read_b128 v[170:173], v179 offset:28672
	ds_read_b128 v[174:177], v179 offset:30720
	s_add_u32 s28, s28, 0x80
	s_addc_u32 s29, s29, 0
	s_cmpk_eq_i32 s28, 0x1f80
	s_mov_b32 s39, s41
	s_waitcnt lgkmcnt(15)
	v_mfma_f32_16x16x32_bf16 v[60:63], v[76:79], v[104:107], v[60:63]
	v_mfma_f32_16x16x32_bf16 v[56:59], v[100:103], v[104:107], v[56:59]
	v_mfma_f32_16x16x32_bf16 v[24:27], v[76:79], v[108:111], v[24:27]
	v_mfma_f32_16x16x32_bf16 v[20:23], v[100:103], v[108:111], v[20:23]
	v_mfma_f32_16x16x32_bf16 v[52:55], v[112:115], v[104:107], v[52:55]
	v_mfma_f32_16x16x32_bf16 v[16:19], v[112:115], v[108:111], v[16:19]
	s_waitcnt lgkmcnt(14)
	v_mfma_f32_16x16x32_bf16 v[48:51], v[116:119], v[104:107], v[48:51]
	v_mfma_f32_16x16x32_bf16 v[12:15], v[116:119], v[108:111], v[12:15]
	s_waitcnt lgkmcnt(13)
	v_mfma_f32_16x16x32_bf16 v[44:47], v[120:123], v[104:107], v[44:47]
	v_mfma_f32_16x16x32_bf16 v[8:11], v[120:123], v[108:111], v[8:11]
	s_waitcnt lgkmcnt(12)
	v_mfma_f32_16x16x32_bf16 v[40:43], v[124:127], v[104:107], v[40:43]
	v_mfma_f32_16x16x32_bf16 v[4:7], v[124:127], v[108:111], v[4:7]
	s_waitcnt lgkmcnt(11)
	v_mfma_f32_16x16x32_bf16 v[32:35], v[128:131], v[104:107], v[32:35]
	v_mfma_f32_16x16x32_bf16 v[0:3], v[128:131], v[108:111], v[0:3]
	s_waitcnt lgkmcnt(10)
	v_mfma_f32_16x16x32_bf16 v[28:31], v[132:135], v[104:107], v[28:31]
	v_mfma_f32_16x16x32_bf16 v[36:39], v[132:135], v[108:111], v[36:39]
	s_waitcnt lgkmcnt(8)
	v_mfma_f32_16x16x32_bf16 v[60:63], v[136:139], v[146:149], v[60:63]
	s_waitcnt lgkmcnt(7)
	v_mfma_f32_16x16x32_bf16 v[56:59], v[140:143], v[146:149], v[56:59]
	s_waitcnt lgkmcnt(6)
	v_mfma_f32_16x16x32_bf16 v[24:27], v[136:139], v[150:153], v[24:27]
	v_mfma_f32_16x16x32_bf16 v[20:23], v[140:143], v[150:153], v[20:23]
	s_waitcnt lgkmcnt(5)
	v_mfma_f32_16x16x32_bf16 v[52:55], v[154:157], v[146:149], v[52:55]
	v_mfma_f32_16x16x32_bf16 v[16:19], v[154:157], v[150:153], v[16:19]
	s_waitcnt lgkmcnt(4)
	v_mfma_f32_16x16x32_bf16 v[48:51], v[158:161], v[146:149], v[48:51]
	v_mfma_f32_16x16x32_bf16 v[12:15], v[158:161], v[150:153], v[12:15]
	s_waitcnt lgkmcnt(3)
	v_mfma_f32_16x16x32_bf16 v[44:47], v[162:165], v[146:149], v[44:47]
	v_mfma_f32_16x16x32_bf16 v[8:11], v[162:165], v[150:153], v[8:11]
	s_waitcnt lgkmcnt(2)
	v_mfma_f32_16x16x32_bf16 v[40:43], v[166:169], v[146:149], v[40:43]
	v_mfma_f32_16x16x32_bf16 v[4:7], v[166:169], v[150:153], v[4:7]
	s_waitcnt lgkmcnt(1)
	v_mfma_f32_16x16x32_bf16 v[32:35], v[170:173], v[146:149], v[32:35]
	v_mfma_f32_16x16x32_bf16 v[0:3], v[170:173], v[150:153], v[0:3]
	s_waitcnt lgkmcnt(0)
	v_mfma_f32_16x16x32_bf16 v[28:31], v[174:177], v[146:149], v[28:31]
	v_mfma_f32_16x16x32_bf16 v[36:39], v[174:177], v[150:153], v[36:39]
	s_cbranch_scc0 .LBB0_1824
	v_add_u32_e32 v80, s40, v84
	v_add_u32_e32 v81, v80, v85
	s_waitcnt vmcnt(0)
	s_barrier
	ds_read_b128 v[72:75], v81 offset:16384
	v_add3_u32 v99, s40, v85, v86
	ds_read_b128 v[76:79], v81 offset:18432
	ds_read_b128 v[100:103], v99
	ds_read_b128 v[104:107], v99 offset:2048
	ds_read_b128 v[108:111], v81 offset:20480
	ds_read_b128 v[112:115], v81 offset:22528
	ds_read_b128 v[116:119], v81 offset:24576
	ds_read_b128 v[120:123], v81 offset:26624
	ds_read_b128 v[124:127], v81 offset:28672
	ds_read_b128 v[128:131], v81 offset:30720
	v_add_u32_e32 v80, v80, v87
	s_waitcnt lgkmcnt(7)
	v_mfma_f32_16x16x32_bf16 v[60:63], v[72:75], v[100:103], v[60:63]
	s_lshl_b32 s38, s38, 7
	v_mfma_f32_16x16x32_bf16 v[56:59], v[76:79], v[100:103], v[56:59]
	s_waitcnt lgkmcnt(4)
	v_mfma_f32_16x16x32_bf16 v[48:51], v[112:115], v[100:103], v[48:51]
	s_waitcnt lgkmcnt(3)
	v_mfma_f32_16x16x32_bf16 v[44:47], v[116:119], v[100:103], v[44:47]
	s_waitcnt lgkmcnt(2)
	v_mfma_f32_16x16x32_bf16 v[40:43], v[120:123], v[100:103], v[40:43]
	s_waitcnt lgkmcnt(1)
	v_mfma_f32_16x16x32_bf16 v[32:35], v[124:127], v[100:103], v[32:35]
	s_waitcnt lgkmcnt(0)
	v_mfma_f32_16x16x32_bf16 v[28:31], v[128:131], v[100:103], v[28:31]
	v_mfma_f32_16x16x32_bf16 v[24:27], v[72:75], v[104:107], v[24:27]
	ds_read_b128 v[72:75], v80 offset:16384
	v_mfma_f32_16x16x32_bf16 v[52:55], v[108:111], v[100:103], v[52:55]
	v_mfma_f32_16x16x32_bf16 v[20:23], v[76:79], v[104:107], v[20:23]
	v_mfma_f32_16x16x32_bf16 v[16:19], v[108:111], v[104:107], v[16:19]
	v_mfma_f32_16x16x32_bf16 v[12:15], v[112:115], v[104:107], v[12:15]
	v_mfma_f32_16x16x32_bf16 v[8:11], v[116:119], v[104:107], v[8:11]
	v_mfma_f32_16x16x32_bf16 v[4:7], v[120:123], v[104:107], v[4:7]
	v_mfma_f32_16x16x32_bf16 v[0:3], v[124:127], v[104:107], v[0:3]
	v_mfma_f32_16x16x32_bf16 v[100:103], v[128:131], v[104:107], v[36:39]
	s_nop 2
	v_add3_u32 v36, s40, v87, v86
	ds_read_b128 v[76:79], v80 offset:18432
	ds_read_b128 v[104:107], v36
	ds_read_b128 v[108:111], v36 offset:2048
	ds_read_b128 v[128:131], v80 offset:28672
	ds_read_b128 v[132:135], v80 offset:30720
	ds_read_b128 v[112:115], v80 offset:20480
	ds_read_b128 v[116:119], v80 offset:22528
	ds_read_b128 v[120:123], v80 offset:24576
	ds_read_b128 v[124:127], v80 offset:26624
	s_waitcnt lgkmcnt(7)
	v_mfma_f32_16x16x32_bf16 v[60:63], v[72:75], v[104:107], v[60:63]
	s_waitcnt lgkmcnt(5)
	v_mfma_f32_16x16x32_bf16 v[36:39], v[128:131], v[104:107], v[32:35]
	s_waitcnt lgkmcnt(4)
	v_mfma_f32_16x16x32_bf16 v[32:35], v[132:135], v[104:107], v[28:31]
	v_mfma_f32_16x16x32_bf16 v[28:31], v[72:75], v[108:111], v[24:27]
	v_add_u32_e32 v72, s38, v83
	v_mul_hi_i32 v73, v72, s31
	v_mfma_f32_16x16x32_bf16 v[24:27], v[76:79], v[108:111], v[20:23]
	s_waitcnt lgkmcnt(3)
	v_mfma_f32_16x16x32_bf16 v[20:23], v[112:115], v[108:111], v[16:19]
	s_waitcnt lgkmcnt(2)
	v_mfma_f32_16x16x32_bf16 v[16:19], v[116:119], v[108:111], v[12:15]
	s_waitcnt lgkmcnt(1)
	v_mfma_f32_16x16x32_bf16 v[12:15], v[120:123], v[108:111], v[8:11]
	s_waitcnt lgkmcnt(0)
	v_mfma_f32_16x16x32_bf16 v[8:11], v[124:127], v[108:111], v[4:7]
	s_nop 2
	v_lshrrev_b32_e32 v4, 31, v73
	v_ashrrev_i32_e32 v5, 11, v73
	v_mfma_f32_16x16x32_bf16 v[56:59], v[76:79], v[104:107], v[56:59]
	v_add_u32_e32 v73, v5, v4
	v_mad_i32_i24 v78, v73, s33, v72
	v_lshlrev_b32_e32 v75, 13, v73
	v_mfma_f32_16x16x32_bf16 v[52:55], v[112:115], v[104:107], v[52:55]
	v_cmp_lt_i32_e32 vcc, s34, v78
	v_add3_u32 v74, v75, v78, s35
	v_mfma_f32_16x16x32_bf16 v[48:51], v[116:119], v[104:107], v[48:51]
	v_mfma_f32_16x16x32_bf16 v[44:47], v[120:123], v[104:107], v[44:47]
	v_mfma_f32_16x16x32_bf16 v[40:43], v[124:127], v[104:107], v[40:43]
	v_mfma_f32_16x16x32_bf16 v[4:7], v[128:131], v[108:111], v[0:3]
	v_mfma_f32_16x16x32_bf16 v[0:3], v[132:135], v[108:111], v[100:103]
	s_and_saveexec_b64 s[28:29], vcc
	s_xor_b64 s[28:29], exec, s[28:29]
	v_add3_u32 v72, v75, v78, s35
	s_or_saveexec_b64 s[28:29], s[28:29]
	v_mov_b64_e32 v[76:77], s[92:93]
	v_lshl_add_u32 v75, v73, 8, v78
	s_xor_b64 exec, exec, s[28:29]
	v_lshl_add_u32 v72, v73, 8, v78
	v_mov_b64_e32 v[76:77], s[2:3]
	s_or_b64 exec, exec, s[28:29]
	s_and_saveexec_b64 s[28:29], vcc
	s_xor_b64 s[28:29], exec, s[28:29]
	s_cbranch_execz .LBB0_1831
	v_add_u32_e32 v73, 3, v73
	v_mul_hi_i32_i24_e32 v79, 0x6000, v73
	v_mul_i32_i24_e32 v78, 0x6000, v73
	s_or_saveexec_b64 s[28:29], s[28:29]
	v_mov_b64_e32 v[80:81], s[92:93]
	s_xor_b64 exec, exec, s[28:29]
	s_cbranch_execnz .LBB0_1832
	s_branch .LBB0_1833
